# code placement: the six GEMM K-loop heads and the attention main-loop head aligned to 64 bytes (.p2align 6); on top of all54
# baseline (speedup 1.0000x reference)
; template <class Epi, class Sched, bool ALIGN_EPI = false, bool SP2 = false>
; __device__ __forceinline__ void gemm_phase(PG8_LAS unsigned char* lds, const Gemm g, const Sched& S, const Epi& E, const int wid) {
;     ...
;         const bool has_next = S.next(ui + 1, nxt);
;         const char* nA = has_next ? (const char*)g.A + (size_t)nxt.pm * tstep : cA; const char* nB = has_next ? (const char*)g.Bt + (size_t)nxt.pn * tstep : cB;
.LBB0_268:
	s_ashr_i32 s15, s14, 31
	s_lshl_b64 s[16:17], s[14:15], 19
	s_add_u32 s16, s80, s16
	s_addc_u32 s17, s81, s17
	s_and_b64 s[18:19], s[4:5], exec
	s_cselect_b32 s15, s17, s23
	s_cselect_b32 s44, s16, s22
	s_ashr_i32 s13, s12, 31
	s_lshl_b64 s[18:19], s[12:13], 19
	s_add_u32 s18, s10, s18
	s_addc_u32 s19, s11, s19
	s_and_b64 s[26:27], s[4:5], exec
	s_cselect_b32 s13, s19, s25
	s_cselect_b32 s45, s18, s24
	s_add_u32 s22, s22, 0x40080
	s_addc_u32 s23, s23, 0
	s_add_u32 s46, s24, 0x100

; template <class Epi, class Sched, bool ALIGN_EPI = false, bool SP2 = false>
; __device__ __forceinline__ void gemm_phase(PG8_LAS unsigned char* lds, const Gemm g, const Sched& S, const Epi& E, const int wid) {
;     ...
;         const char* nA = has_next ? (const char*)g.A + (size_t)nxt.pm * tstep : cA; const char* nB = has_next ? (const char*)g.Bt + (size_t)nxt.pn * tstep : cB;
;         for (int t = 0; t < nt; t += 2) {
	s_addc_u32 s47, s25, 0
	s_mov_b32 s48, -2


; #define PG8_STAGE(bufoff, gbase, voff) do { _Pragma("unroll") for (int _i = 0; _i < 2; ++_i) \
;         __builtin_amdgcn_global_load_lds((const unsigned*)((const char*)(gbase) + (voff)[_i]), (PG8_LAS unsigned*)(lds + (bufoff) + ldsw + _i * 8192), 16, 0, 0); } while (0)
; #define PG8_LDA(dst, b, h) do { _Pragma("unroll") for (int m = 0; m < 4; ++m) _Pragma("unroll") for (int k = 0; k < 2; ++k) dst[m][k] = *(const PG8_LAS bf16x8*)(lds + PG8_SA(b, h) + aoff + m * 2048 + k * 1024); } while (0)
; #define PG8_LDB(dst, b, h) do { _Pragma("unroll") for (int n = 0; n < 2; ++n) _Pragma("unroll") for (int k = 0; k < 2; ++k) dst[n][k] = *(const PG8_LAS bf16x8*)(lds + PG8_SB(b, h) + boff + n * 2048 + k * 1024); } while (0)
; #define PG8_MMA(ai, bj, At, Bt) do { __builtin_amdgcn_s_setprio(1); _Pragma("unroll") for (int m = 0; m < 4; ++m) _Pragma("unroll") for (int n = 0; n < 2; ++n) _Pragma("unroll") for (int k = 0; k < 2; ++k) \
;         acc[ai][bj][m][n] = __builtin_amdgcn_mfma_f32_16x16x32_bf16(Bt[n][k], At[m][k], acc[ai][bj][m][n], 0, 0, 0); __builtin_amdgcn_s_setprio(0); } while (0)
; #define PG8_WAIT_V(n) asm volatile("s_waitcnt vmcnt(" #n ")" ::: "memory")
; #define PG8_WAIT_L(n) asm volatile("s_waitcnt lgkmcnt(" #n ")" ::: "memory")
; #define PG8_BAR __builtin_amdgcn_s_barrier()
; #define PG8_SCHED __builtin_amdgcn_sched_barrier(0)
; template <class Epi, class Sched, bool ALIGN_EPI = false, bool SP2 = false>
; __device__ __forceinline__ void gemm_phase(PG8_LAS unsigned char* lds, const Gemm g, const Sched& S, const Epi& E, const int wid) {
;     ...
;             PG8_LDB(B0, 0, 0); PG8_LDB(B1, 0, 1); PG8_SCHED; PG8_LDA(At, 0, 0); PG8_STAGE(PG8_SA(1, 1), a1 + hstep, voffA);
;             PG8_WAIT_V(8); PG8_WAIT_L(0); PG8_BAR; PG8_MMA(0, 0, At, B0); PG8_MMA(0, 1, At, B1); PG8_BAR; PG8_SCHED;
;             PG8_LDA(At, 0, 1); PG8_STAGE(PG8_SB(0, 0), b2, voffB); PG8_STAGE(PG8_SB(0, 1), b2 + hstep, voffB); PG8_STAGE(PG8_SA(0, 0), a2, voffA);
;             PG8_WAIT_V(8); PG8_WAIT_L(0); PG8_BAR; PG8_MMA(1, 0, At, B0); PG8_MMA(1, 1, At, B1); PG8_BAR; PG8_SCHED;
	ds_read_b128 v[144:147], v151
	ds_read_b128 v[154:157], v151 offset:1024
	ds_read_b128 v[158:161], v151 offset:2048
	ds_read_b128 v[162:165], v151 offset:3072
	ds_read_b128 v[166:169], v152
	ds_read_b128 v[170:173], v152 offset:1024
	ds_read_b128 v[174:177], v152 offset:2048
	ds_read_b128 v[178:181], v152 offset:3072
	s_add_u32 s24, s22, 0xfffc0080
	s_addc_u32 s25, s23, -1
	s_cmp_eq_u32 s48, 12
	s_cselect_b32 s27, s15, s25
	s_cselect_b32 s26, s44, s24
	s_cselect_b32 s25, s13, s47
	s_cselect_b32 s24, s45, s46
	v_lshl_add_u64 v[206:207], s[22:23], 0, v[136:137]
	s_add_i32 m0, s21, 0xc000
	ds_read_b128 v[182:185], v153
	ds_read_b128 v[186:189], v153 offset:1024
	ds_read_b128 v[190:193], v153 offset:2048
	ds_read_b128 v[194:197], v153 offset:3072
	ds_read_b128 v[198:201], v153 offset:4096
	ds_read_b128 v[202:205], v153 offset:5120
	ds_read_b128 v[212:215], v153 offset:6144
	ds_read_b128 v[216:219], v153 offset:7168
	global_load_lds_dwordx4 v[206:207], off
	v_lshl_add_u64 v[206:207], s[22:23], 0, v[138:139]
	s_add_i32 m0, s21, 0xe000
	s_nop 0
	global_load_lds_dwordx4 v[206:207], off
	s_waitcnt vmcnt(8)
	s_waitcnt lgkmcnt(0)
	s_barrier
	s_waitcnt lgkmcnt(0)
	v_mfma_f32_16x16x32_bf16 v[124:127], v[144:147], v[182:185], 0
	v_mfma_f32_16x16x32_bf16 v[116:119], v[158:161], v[182:185], 0
	v_mfma_f32_16x16x32_bf16 v[108:111], v[144:147], v[190:193], 0
	v_mfma_f32_16x16x32_bf16 v[100:103], v[158:161], v[190:193], 0
	v_mfma_f32_16x16x32_bf16 v[92:95], v[144:147], v[198:201], 0
	v_mfma_f32_16x16x32_bf16 v[84:87], v[158:161], v[198:201], 0
	v_mfma_f32_16x16x32_bf16 v[76:79], v[144:147], v[212:215], 0
	v_mfma_f32_16x16x32_bf16 v[68:71], v[158:161], v[212:215], 0
	v_mfma_f32_16x16x32_bf16 v[124:127], v[154:157], v[186:189], v[124:127]
	v_mfma_f32_16x16x32_bf16 v[116:119], v[162:165], v[186:189], v[116:119]
	v_mfma_f32_16x16x32_bf16 v[108:111], v[154:157], v[194:197], v[108:111]
	v_mfma_f32_16x16x32_bf16 v[100:103], v[162:165], v[194:197], v[100:103]
	v_mfma_f32_16x16x32_bf16 v[92:95], v[154:157], v[202:205], v[92:95]
	v_mfma_f32_16x16x32_bf16 v[84:87], v[162:165], v[202:205], v[84:87]
	v_mfma_f32_16x16x32_bf16 v[76:79], v[154:157], v[216:219], v[76:79]
	v_mfma_f32_16x16x32_bf16 v[68:71], v[162:165], v[216:219], v[68:71]
	v_mfma_f32_16x16x32_bf16 v[120:123], v[166:169], v[182:185], 0
	v_mfma_f32_16x16x32_bf16 v[112:115], v[174:177], v[182:185], 0
	v_mfma_f32_16x16x32_bf16 v[104:107], v[166:169], v[190:193], 0
	v_mfma_f32_16x16x32_bf16 v[96:99], v[174:177], v[190:193], 0
	v_mfma_f32_16x16x32_bf16 v[88:91], v[166:169], v[198:201], 0
	v_mfma_f32_16x16x32_bf16 v[80:83], v[174:177], v[198:201], 0
	v_mfma_f32_16x16x32_bf16 v[72:75], v[166:169], v[212:215], 0
	v_mfma_f32_16x16x32_bf16 v[64:67], v[174:177], v[212:215], 0
	v_mfma_f32_16x16x32_bf16 v[120:123], v[170:173], v[186:189], v[120:123]
	v_mfma_f32_16x16x32_bf16 v[112:115], v[178:181], v[186:189], v[112:115]
	v_mfma_f32_16x16x32_bf16 v[104:107], v[170:173], v[194:197], v[104:107]
	v_mfma_f32_16x16x32_bf16 v[96:99], v[178:181], v[194:197], v[96:99]
	v_mfma_f32_16x16x32_bf16 v[88:91], v[170:173], v[202:205], v[88:91]
	v_mfma_f32_16x16x32_bf16 v[80:83], v[178:181], v[202:205], v[80:83]
	v_mfma_f32_16x16x32_bf16 v[72:75], v[170:173], v[216:219], v[72:75]
	v_mfma_f32_16x16x32_bf16 v[64:67], v[178:181], v[216:219], v[64:67]
	s_barrier
	s_add_i32 s49, s40, s9
	v_lshl_add_u64 v[206:207], s[24:25], 0, v[132:133]
	s_mov_b32 m0, s49
	ds_read_b128 v[182:185], v153 offset:16384
	ds_read_b128 v[186:189], v153 offset:17408
	ds_read_b128 v[190:193], v153 offset:18432
	ds_read_b128 v[194:197], v153 offset:19456
	ds_read_b128 v[198:201], v153 offset:20480
	ds_read_b128 v[202:205], v153 offset:21504
	ds_read_b128 v[212:215], v153 offset:22528
	ds_read_b128 v[216:219], v153 offset:23552
	global_load_lds_dwordx4 v[206:207], off
	s_add_i32 m0, s49, 0x2000
	s_add_u32 s50, s24, 0x40000
	v_lshl_add_u64 v[220:221], s[24:25], 0, v[128:129]
	s_addc_u32 s51, s25, 0
	s_add_i32 s49, s41, s9
	global_load_lds_dwordx4 v[220:221], off
	v_lshl_add_u64 v[222:223], s[50:51], 0, v[132:133]
	s_mov_b32 m0, s49
	v_lshl_add_u64 v[224:225], s[26:27], 0, v[130:131]
	global_load_lds_dwordx4 v[222:223], off
	v_lshl_add_u64 v[222:223], s[50:51], 0, v[128:129]
	s_add_i32 m0, s49, 0x2000
	s_nop 0
	global_load_lds_dwordx4 v[222:223], off
	v_lshl_add_u64 v[222:223], s[26:27], 0, v[134:135]
	s_mov_b32 m0, s21
	s_nop 0
	global_load_lds_dwordx4 v[222:223], off
	s_mov_b32 m0, s30
	s_nop 0
	global_load_lds_dwordx4 v[224:225], off
	s_waitcnt vmcnt(8)
	s_waitcnt lgkmcnt(0)
	s_barrier
	s_waitcnt lgkmcnt(0)
	v_mfma_f32_16x16x32_bf16 v[60:63], v[144:147], v[182:185], 0
	v_mfma_f32_16x16x32_bf16 v[52:55], v[158:161], v[182:185], 0
	v_mfma_f32_16x16x32_bf16 v[44:47], v[144:147], v[190:193], 0
	v_mfma_f32_16x16x32_bf16 v[36:39], v[158:161], v[190:193], 0
	v_mfma_f32_16x16x32_bf16 v[28:31], v[144:147], v[198:201], 0
	v_mfma_f32_16x16x32_bf16 v[20:23], v[158:161], v[198:201], 0
	v_mfma_f32_16x16x32_bf16 v[12:15], v[144:147], v[212:215], 0
	v_mfma_f32_16x16x32_bf16 v[4:7], v[158:161], v[212:215], 0
	v_mfma_f32_16x16x32_bf16 v[60:63], v[154:157], v[186:189], v[60:63]
	v_mfma_f32_16x16x32_bf16 v[52:55], v[162:165], v[186:189], v[52:55]
	v_mfma_f32_16x16x32_bf16 v[44:47], v[154:157], v[194:197], v[44:47]
	v_mfma_f32_16x16x32_bf16 v[36:39], v[162:165], v[194:197], v[36:39]
	v_mfma_f32_16x16x32_bf16 v[28:31], v[154:157], v[202:205], v[28:31]
	v_mfma_f32_16x16x32_bf16 v[20:23], v[162:165], v[202:205], v[20:23]
	v_mfma_f32_16x16x32_bf16 v[12:15], v[154:157], v[216:219], v[12:15]
	v_mfma_f32_16x16x32_bf16 v[4:7], v[162:165], v[216:219], v[4:7]
	v_mfma_f32_16x16x32_bf16 v[56:59], v[166:169], v[182:185], 0
	v_mfma_f32_16x16x32_bf16 v[48:51], v[174:177], v[182:185], 0
	v_mfma_f32_16x16x32_bf16 v[40:43], v[166:169], v[190:193], 0
	v_mfma_f32_16x16x32_bf16 v[32:35], v[174:177], v[190:193], 0
	v_mfma_f32_16x16x32_bf16 v[24:27], v[166:169], v[198:201], 0
	v_mfma_f32_16x16x32_bf16 v[16:19], v[174:177], v[198:201], 0
	v_mfma_f32_16x16x32_bf16 v[8:11], v[166:169], v[212:215], 0
	v_mfma_f32_16x16x32_bf16 v[0:3], v[174:177], v[212:215], 0
	v_mfma_f32_16x16x32_bf16 v[56:59], v[170:173], v[186:189], v[56:59]
	v_mfma_f32_16x16x32_bf16 v[48:51], v[178:181], v[186:189], v[48:51]
	v_mfma_f32_16x16x32_bf16 v[40:43], v[170:173], v[194:197], v[40:43]
	v_mfma_f32_16x16x32_bf16 v[32:35], v[178:181], v[194:197], v[32:35]
	v_mfma_f32_16x16x32_bf16 v[24:27], v[170:173], v[202:205], v[24:27]
	v_mfma_f32_16x16x32_bf16 v[16:19], v[178:181], v[202:205], v[16:19]
	v_mfma_f32_16x16x32_bf16 v[8:11], v[170:173], v[216:219], v[8:11]
	v_mfma_f32_16x16x32_bf16 v[0:3], v[178:181], v[216:219], v[0:3]
	s_barrier
; #define PG8_STAGE(bufoff, gbase, voff) do { _Pragma("unroll") for (int _i = 0; _i < 2; ++_i) \
;         __builtin_amdgcn_global_load_lds((const unsigned*)((const char*)(gbase) + (voff)[_i]), (PG8_LAS unsigned*)(lds + (bufoff) + ldsw + _i * 8192), 16, 0, 0); } while (0)
; #define PG8_LDA(dst, b, h) do { _Pragma("unroll") for (int m = 0; m < 4; ++m) _Pragma("unroll") for (int k = 0; k < 2; ++k) dst[m][k] = *(const PG8_LAS bf16x8*)(lds + PG8_SA(b, h) + aoff + m * 2048 + k * 1024); } while (0)
; #define PG8_LDB(dst, b, h) do { _Pragma("unroll") for (int n = 0; n < 2; ++n) _Pragma("unroll") for (int k = 0; k < 2; ++k) dst[n][k] = *(const PG8_LAS bf16x8*)(lds + PG8_SB(b, h) + boff + n * 2048 + k * 1024); } while (0)
; #define PG8_MMA(ai, bj, At, Bt) do { __builtin_amdgcn_s_setprio(1); _Pragma("unroll") for (int m = 0; m < 4; ++m) _Pragma("unroll") for (int n = 0; n < 2; ++n) _Pragma("unroll") for (int k = 0; k < 2; ++k) \
;         acc[ai][bj][m][n] = __builtin_amdgcn_mfma_f32_16x16x32_bf16(Bt[n][k], At[m][k], acc[ai][bj][m][n], 0, 0, 0); __builtin_amdgcn_s_setprio(0); } while (0)
; #define PG8_WAIT_V(n) asm volatile("s_waitcnt vmcnt(" #n ")" ::: "memory")
; #define PG8_WAIT_L(n) asm volatile("s_waitcnt lgkmcnt(" #n ")" ::: "memory")
; #define PG8_BAR __builtin_amdgcn_s_barrier()
; #define PG8_SCHED __builtin_amdgcn_sched_barrier(0)
; template <class Epi, class Sched, bool ALIGN_EPI = false, bool SP2 = false>
; __device__ __forceinline__ void gemm_phase(PG8_LAS unsigned char* lds, const Gemm g, const Sched& S, const Epi& E, const int wid) {
;     ...
;             PG8_LDB(B0, 1, 0); PG8_LDB(B1, 1, 1); PG8_SCHED; PG8_LDA(At, 1, 0); PG8_STAGE(PG8_SA(0, 1), a2 + hstep, voffA);
;             PG8_WAIT_V(8); PG8_WAIT_L(0); PG8_BAR; PG8_MMA(0, 0, At, B0); PG8_MMA(0, 1, At, B1); PG8_BAR; PG8_SCHED;
	s_add_i32 s49, 0, 0x18000
	s_add_i32 s50, 0, 0x1c000
	v_add_u32_e32 v162, s49, v149
	v_add_u32_e32 v178, s50, v149
	ds_read_b128 v[144:147], v162
	ds_read_b128 v[154:157], v162 offset:1024
	ds_read_b128 v[158:161], v162 offset:2048
	ds_read_b128 v[162:165], v162 offset:3072
	ds_read_b128 v[166:169], v178
	ds_read_b128 v[170:173], v178 offset:1024
	ds_read_b128 v[174:177], v178 offset:2048
	ds_read_b128 v[178:181], v178 offset:3072
	s_add_u32 s26, s26, 0x40000
	s_addc_u32 s27, s27, 0
	s_mov_b32 m0, s31
	v_lshl_add_u64 v[226:227], s[26:27], 0, v[134:135]
	ds_read_b128 v[182:185], v153 offset:32768
	ds_read_b128 v[186:189], v153 offset:33792
	ds_read_b128 v[190:193], v153 offset:34816
	ds_read_b128 v[194:197], v153 offset:35840
	ds_read_b128 v[198:201], v153 offset:36864
	ds_read_b128 v[202:205], v153 offset:37888
	ds_read_b128 v[212:215], v153 offset:38912
	ds_read_b128 v[216:219], v153 offset:39936
	global_load_lds_dwordx4 v[226:227], off
	v_lshl_add_u64 v[226:227], s[26:27], 0, v[130:131]
	s_mov_b32 m0, s33
	s_nop 0
	global_load_lds_dwordx4 v[226:227], off
	s_waitcnt vmcnt(8)
	s_waitcnt lgkmcnt(0)
	s_barrier
	s_waitcnt lgkmcnt(0)
	v_mfma_f32_16x16x32_bf16 v[124:127], v[144:147], v[182:185], v[124:127]
	v_mfma_f32_16x16x32_bf16 v[116:119], v[158:161], v[182:185], v[116:119]
	v_mfma_f32_16x16x32_bf16 v[108:111], v[144:147], v[190:193], v[108:111]
	v_mfma_f32_16x16x32_bf16 v[100:103], v[158:161], v[190:193], v[100:103]
	v_mfma_f32_16x16x32_bf16 v[92:95], v[144:147], v[198:201], v[92:95]
	v_mfma_f32_16x16x32_bf16 v[84:87], v[158:161], v[198:201], v[84:87]
	v_mfma_f32_16x16x32_bf16 v[76:79], v[144:147], v[212:215], v[76:79]
	v_mfma_f32_16x16x32_bf16 v[68:71], v[158:161], v[212:215], v[68:71]
	v_mfma_f32_16x16x32_bf16 v[124:127], v[154:157], v[186:189], v[124:127]
	v_mfma_f32_16x16x32_bf16 v[116:119], v[162:165], v[186:189], v[116:119]
	v_mfma_f32_16x16x32_bf16 v[108:111], v[154:157], v[194:197], v[108:111]
	v_mfma_f32_16x16x32_bf16 v[100:103], v[162:165], v[194:197], v[100:103]
	v_mfma_f32_16x16x32_bf16 v[92:95], v[154:157], v[202:205], v[92:95]
	v_mfma_f32_16x16x32_bf16 v[84:87], v[162:165], v[202:205], v[84:87]
	v_mfma_f32_16x16x32_bf16 v[76:79], v[154:157], v[216:219], v[76:79]
	v_mfma_f32_16x16x32_bf16 v[68:71], v[162:165], v[216:219], v[68:71]
	v_mfma_f32_16x16x32_bf16 v[120:123], v[166:169], v[182:185], v[120:123]
	v_mfma_f32_16x16x32_bf16 v[112:115], v[174:177], v[182:185], v[112:115]
	v_mfma_f32_16x16x32_bf16 v[104:107], v[166:169], v[190:193], v[104:107]
	v_mfma_f32_16x16x32_bf16 v[96:99], v[174:177], v[190:193], v[96:99]
	v_mfma_f32_16x16x32_bf16 v[88:91], v[166:169], v[198:201], v[88:91]
	v_mfma_f32_16x16x32_bf16 v[80:83], v[174:177], v[198:201], v[80:83]
	v_mfma_f32_16x16x32_bf16 v[72:75], v[166:169], v[212:215], v[72:75]
	v_mfma_f32_16x16x32_bf16 v[64:67], v[174:177], v[212:215], v[64:67]
	v_mfma_f32_16x16x32_bf16 v[120:123], v[170:173], v[186:189], v[120:123]
	v_mfma_f32_16x16x32_bf16 v[112:115], v[178:181], v[186:189], v[112:115]
	v_mfma_f32_16x16x32_bf16 v[104:107], v[170:173], v[194:197], v[104:107]
	v_mfma_f32_16x16x32_bf16 v[96:99], v[178:181], v[194:197], v[96:99]
	v_mfma_f32_16x16x32_bf16 v[88:91], v[170:173], v[202:205], v[88:91]
	v_mfma_f32_16x16x32_bf16 v[80:83], v[178:181], v[202:205], v[80:83]
	v_mfma_f32_16x16x32_bf16 v[72:75], v[170:173], v[216:219], v[72:75]
	v_mfma_f32_16x16x32_bf16 v[64:67], v[178:181], v[216:219], v[64:67]
	s_barrier
; #define PG8_STAGE(bufoff, gbase, voff) do { _Pragma("unroll") for (int _i = 0; _i < 2; ++_i) \
;         __builtin_amdgcn_global_load_lds((const unsigned*)((const char*)(gbase) + (voff)[_i]), (PG8_LAS unsigned*)(lds + (bufoff) + ldsw + _i * 8192), 16, 0, 0); } while (0)
; #define PG8_LDA(dst, b, h) do { _Pragma("unroll") for (int m = 0; m < 4; ++m) _Pragma("unroll") for (int k = 0; k < 2; ++k) dst[m][k] = *(const PG8_LAS bf16x8*)(lds + PG8_SA(b, h) + aoff + m * 2048 + k * 1024); } while (0)
; #define PG8_MMA(ai, bj, At, Bt) do { __builtin_amdgcn_s_setprio(1); _Pragma("unroll") for (int m = 0; m < 4; ++m) _Pragma("unroll") for (int n = 0; n < 2; ++n) _Pragma("unroll") for (int k = 0; k < 2; ++k) \
;         acc[ai][bj][m][n] = __builtin_amdgcn_mfma_f32_16x16x32_bf16(Bt[n][k], At[m][k], acc[ai][bj][m][n], 0, 0, 0); __builtin_amdgcn_s_setprio(0); } while (0)
; #define PG8_WAIT_V(n) asm volatile("s_waitcnt vmcnt(" #n ")" ::: "memory")
; #define PG8_WAIT_L(n) asm volatile("s_waitcnt lgkmcnt(" #n ")" ::: "memory")
; #define PG8_BAR __builtin_amdgcn_s_barrier()
; #define PG8_SCHED __builtin_amdgcn_sched_barrier(0)
; template <class Epi, class Sched, bool ALIGN_EPI = false, bool SP2 = false>
; __device__ __forceinline__ void gemm_phase(PG8_LAS unsigned char* lds, const Gemm g, const Sched& S, const Epi& E, const int wid) {
;     ...
;             PG8_LDA(At, 1, 1); PG8_STAGE(PG8_SB(1, 0), b3, voffB); PG8_STAGE(PG8_SB(1, 1), b3 + hstep, voffB); PG8_STAGE(PG8_SA(1, 0), a3, voffA);
;             PG8_WAIT_V(8); PG8_WAIT_L(0); PG8_BAR; PG8_MMA(1, 0, At, B0); PG8_MMA(1, 1, At, B1); PG8_BAR; PG8_SCHED;
	s_add_i32 s26, s49, s9
	v_lshl_add_u64 v[206:207], v[206:207], 0, s[6:7]
	s_mov_b32 m0, s26
	ds_read_b128 v[182:185], v153 offset:49152
	ds_read_b128 v[186:189], v153 offset:50176
	ds_read_b128 v[190:193], v153 offset:51200
	ds_read_b128 v[194:197], v153 offset:52224
	ds_read_b128 v[198:201], v153 offset:53248
	ds_read_b128 v[202:205], v153 offset:54272
	ds_read_b128 v[212:215], v153 offset:55296
	ds_read_b128 v[216:219], v153 offset:56320
	global_load_lds_dwordx4 v[206:207], off
	s_add_i32 m0, s26, 0x2000
	s_add_u32 s24, s24, 0x40080
	v_lshl_add_u64 v[206:207], v[220:221], 0, s[6:7]
	s_addc_u32 s25, s25, 0
	s_add_i32 s26, s50, s9
	global_load_lds_dwordx4 v[206:207], off
	v_lshl_add_u64 v[206:207], s[24:25], 0, v[132:133]
	s_mov_b32 m0, s26
	s_nop 0
	global_load_lds_dwordx4 v[206:207], off
	v_lshl_add_u64 v[206:207], s[24:25], 0, v[128:129]
	s_add_i32 m0, s26, 0x2000
	s_nop 0
	global_load_lds_dwordx4 v[206:207], off
	v_lshl_add_u64 v[206:207], v[222:223], 0, s[6:7]
	s_mov_b32 m0, s38
	s_nop 0
	global_load_lds_dwordx4 v[206:207], off
	v_lshl_add_u64 v[206:207], v[224:225], 0, s[6:7]
	s_mov_b32 m0, s39
	s_nop 0
	global_load_lds_dwordx4 v[206:207], off
	s_waitcnt vmcnt(8)
	s_waitcnt lgkmcnt(0)
	s_barrier
	s_waitcnt lgkmcnt(0)
	v_mfma_f32_16x16x32_bf16 v[60:63], v[144:147], v[182:185], v[60:63]
	v_mfma_f32_16x16x32_bf16 v[52:55], v[158:161], v[182:185], v[52:55]
	v_mfma_f32_16x16x32_bf16 v[44:47], v[144:147], v[190:193], v[44:47]
	v_mfma_f32_16x16x32_bf16 v[36:39], v[158:161], v[190:193], v[36:39]
	v_mfma_f32_16x16x32_bf16 v[28:31], v[144:147], v[198:201], v[28:31]
	v_mfma_f32_16x16x32_bf16 v[20:23], v[158:161], v[198:201], v[20:23]
	v_mfma_f32_16x16x32_bf16 v[12:15], v[144:147], v[212:215], v[12:15]
	v_mfma_f32_16x16x32_bf16 v[4:7], v[158:161], v[212:215], v[4:7]
	v_mfma_f32_16x16x32_bf16 v[60:63], v[154:157], v[186:189], v[60:63]
	v_mfma_f32_16x16x32_bf16 v[52:55], v[162:165], v[186:189], v[52:55]
	v_mfma_f32_16x16x32_bf16 v[44:47], v[154:157], v[194:197], v[44:47]
	v_mfma_f32_16x16x32_bf16 v[36:39], v[162:165], v[194:197], v[36:39]
	v_mfma_f32_16x16x32_bf16 v[28:31], v[154:157], v[202:205], v[28:31]
	v_mfma_f32_16x16x32_bf16 v[20:23], v[162:165], v[202:205], v[20:23]
	v_mfma_f32_16x16x32_bf16 v[12:15], v[154:157], v[216:219], v[12:15]
	v_mfma_f32_16x16x32_bf16 v[4:7], v[162:165], v[216:219], v[4:7]
	v_mfma_f32_16x16x32_bf16 v[56:59], v[166:169], v[182:185], v[56:59]
	v_mfma_f32_16x16x32_bf16 v[48:51], v[174:177], v[182:185], v[48:51]
	v_mfma_f32_16x16x32_bf16 v[40:43], v[166:169], v[190:193], v[40:43]
	v_mfma_f32_16x16x32_bf16 v[32:35], v[174:177], v[190:193], v[32:35]
	v_mfma_f32_16x16x32_bf16 v[24:27], v[166:169], v[198:201], v[24:27]
	v_mfma_f32_16x16x32_bf16 v[16:19], v[174:177], v[198:201], v[16:19]
	v_mfma_f32_16x16x32_bf16 v[8:11], v[166:169], v[212:215], v[8:11]
	v_mfma_f32_16x16x32_bf16 v[0:3], v[174:177], v[212:215], v[0:3]
	v_mfma_f32_16x16x32_bf16 v[56:59], v[170:173], v[186:189], v[56:59]
	v_mfma_f32_16x16x32_bf16 v[48:51], v[178:181], v[186:189], v[48:51]
	v_mfma_f32_16x16x32_bf16 v[40:43], v[170:173], v[194:197], v[40:43]
	v_mfma_f32_16x16x32_bf16 v[32:35], v[178:181], v[194:197], v[32:35]
	v_mfma_f32_16x16x32_bf16 v[24:27], v[170:173], v[202:205], v[24:27]
	v_mfma_f32_16x16x32_bf16 v[16:19], v[178:181], v[202:205], v[16:19]
	v_mfma_f32_16x16x32_bf16 v[8:11], v[170:173], v[216:219], v[8:11]
	v_mfma_f32_16x16x32_bf16 v[0:3], v[178:181], v[216:219], v[0:3]
	s_barrier
	s_add_i32 s48, s48, 2
	s_add_u32 s22, s22, 0x100
	s_addc_u32 s23, s23, 0
	s_add_u32 s46, s46, 0x100
	s_addc_u32 s47, s47, 0
	s_cmp_gt_u32 s48, 13
	s_cbranch_scc0 .LBB0_269
	s_branch .Lkp_exit_0
	.p2align 6

; template <class Epi, class Sched, bool ALIGN_EPI = false, bool SP2 = false>
; __device__ __forceinline__ void gemm_phase(PG8_LAS unsigned char* lds, const Gemm g, const Sched& S, const Epi& E, const int wid) {
;     ...
;         const char* nA = has_next ? (const char*)g.A + (size_t)nxt.pm * tstep : cA; const char* nB = has_next ? (const char*)g.Bt + (size_t)nxt.pn * tstep : cB;
;         for (int t = 0; t < nt; t += 2) {
;             const bool last = (t == nt - 2);
;             const char* a1 = cA + (size_t)(t + 1) * kstep;
;             const char* a2 = last ? nA : cA + (size_t)(t + 2) * kstep; const char* b2 = last ? nB : cB + (size_t)(t + 2) * kstep;
;             const char* a3 = a2 + kstep; const char* b3 = b2 + kstep;
.LBB0_755:
	s_add_u32 s42, s14, 0x100
	s_addc_u32 s43, s15, 0
	v_lshl_add_u64 v[144:145], s[2:3], 0, v[136:137]
	v_lshl_add_u64 v[146:147], s[2:3], 0, v[138:139]
	s_mov_b32 s44, -2
	s_mov_b64 s[14:15], 0
	.p2align 6

; template <class Epi, class Sched, bool ALIGN_EPI = false, bool SP2 = false>
; __device__ __forceinline__ void gemm_phase(PG8_LAS unsigned char* lds, const Gemm g, const Sched& S, const Epi& E, const int wid) {
;     ...
;         const bool has_next = S.next(ui + 1, nxt);
;         const char* nA = has_next ? (const char*)g.A + (size_t)nxt.pm * tstep : cA; const char* nB = has_next ? (const char*)g.Bt + (size_t)nxt.pn * tstep : cB;
.LBB0_881:
	s_ashr_i32 s13, s12, 31
	s_lshl_b64 s[14:15], s[12:13], 19
	s_add_u32 s14, s80, s14
	s_addc_u32 s15, s81, s15
	s_and_b64 s[18:19], s[4:5], exec
	s_cselect_b32 s13, s15, s21
	s_cselect_b32 s43, s14, s20
	s_ashr_i32 s9, s8, 31
	s_lshl_b64 s[18:19], s[8:9], 19
	s_add_u32 s18, s10, s18
	s_addc_u32 s19, s11, s19
	s_and_b64 s[24:25], s[4:5], exec
	s_cselect_b32 s9, s19, s23
	s_cselect_b32 s44, s18, s22
	s_add_u32 s20, s20, 0x40080
	s_addc_u32 s21, s21, 0
	s_add_u32 s45, s22, 0x100

; template <class Epi, class Sched, bool ALIGN_EPI = false, bool SP2 = false>
; __device__ __forceinline__ void gemm_phase(PG8_LAS unsigned char* lds, const Gemm g, const Sched& S, const Epi& E, const int wid) {
;     ...
;         const char* nA = has_next ? (const char*)g.A + (size_t)nxt.pm * tstep : cA; const char* nB = has_next ? (const char*)g.Bt + (size_t)nxt.pn * tstep : cB;
;         for (int t = 0; t < nt; t += 2) {
	s_addc_u32 s46, s23, 0
	s_mov_b32 s47, -2


; #define PG8_STAGE(bufoff, gbase, voff) do { _Pragma("unroll") for (int _i = 0; _i < 2; ++_i) \
;         __builtin_amdgcn_global_load_lds((const unsigned*)((const char*)(gbase) + (voff)[_i]), (PG8_LAS unsigned*)(lds + (bufoff) + ldsw + _i * 8192), 16, 0, 0); } while (0)
; #define PG8_LDA(dst, b, h) do { _Pragma("unroll") for (int m = 0; m < 4; ++m) _Pragma("unroll") for (int k = 0; k < 2; ++k) dst[m][k] = *(const PG8_LAS bf16x8*)(lds + PG8_SA(b, h) + aoff + m * 2048 + k * 1024); } while (0)
; #define PG8_LDB(dst, b, h) do { _Pragma("unroll") for (int n = 0; n < 2; ++n) _Pragma("unroll") for (int k = 0; k < 2; ++k) dst[n][k] = *(const PG8_LAS bf16x8*)(lds + PG8_SB(b, h) + boff + n * 2048 + k * 1024); } while (0)
; #define PG8_MMA(ai, bj, At, Bt) do { __builtin_amdgcn_s_setprio(1); _Pragma("unroll") for (int m = 0; m < 4; ++m) _Pragma("unroll") for (int n = 0; n < 2; ++n) _Pragma("unroll") for (int k = 0; k < 2; ++k) \
;         acc[ai][bj][m][n] = __builtin_amdgcn_mfma_f32_16x16x32_bf16(Bt[n][k], At[m][k], acc[ai][bj][m][n], 0, 0, 0); __builtin_amdgcn_s_setprio(0); } while (0)
; #define PG8_WAIT_V(n) asm volatile("s_waitcnt vmcnt(" #n ")" ::: "memory")
; #define PG8_WAIT_L(n) asm volatile("s_waitcnt lgkmcnt(" #n ")" ::: "memory")
; #define PG8_BAR __builtin_amdgcn_s_barrier()
; #define PG8_SCHED __builtin_amdgcn_sched_barrier(0)
; template <class Epi, class Sched, bool ALIGN_EPI = false, bool SP2 = false>
; __device__ __forceinline__ void gemm_phase(PG8_LAS unsigned char* lds, const Gemm g, const Sched& S, const Epi& E, const int wid) {
;     ...
;             PG8_LDB(B0, 0, 0); PG8_LDB(B1, 0, 1); PG8_SCHED; PG8_LDA(At, 0, 0); PG8_STAGE(PG8_SA(1, 1), a1 + hstep, voffA);
;             PG8_WAIT_V(8); PG8_WAIT_L(0); PG8_BAR; PG8_MMA(0, 0, At, B0); PG8_MMA(0, 1, At, B1); PG8_BAR; PG8_SCHED;
;             PG8_LDA(At, 0, 1); PG8_STAGE(PG8_SB(0, 0), b2, voffB); PG8_STAGE(PG8_SB(0, 1), b2 + hstep, voffB); PG8_STAGE(PG8_SA(0, 0), a2, voffA);
;             PG8_WAIT_V(8); PG8_WAIT_L(0); PG8_BAR; PG8_MMA(1, 0, At, B0); PG8_MMA(1, 1, At, B1); PG8_BAR; PG8_SCHED;
	ds_read_b128 v[152:155], v149
	ds_read_b128 v[156:159], v149 offset:1024
	ds_read_b128 v[160:163], v149 offset:2048
	ds_read_b128 v[164:167], v149 offset:3072
	ds_read_b128 v[168:171], v150
	ds_read_b128 v[172:175], v150 offset:1024
	ds_read_b128 v[176:179], v150 offset:2048
	ds_read_b128 v[180:183], v150 offset:3072
	s_add_u32 s22, s20, 0xfffc0080
	s_addc_u32 s23, s21, -1
	s_cmp_eq_u32 s47, 12
	s_cselect_b32 s25, s13, s23
	s_cselect_b32 s24, s43, s22
	s_cselect_b32 s23, s9, s46
	s_cselect_b32 s22, s44, s45
	v_lshl_add_u64 v[144:145], s[20:21], 0, v[136:137]
	s_add_i32 m0, s17, 0xc000
	ds_read_b128 v[184:187], v151
	ds_read_b128 v[188:191], v151 offset:1024
	ds_read_b128 v[192:195], v151 offset:2048
	ds_read_b128 v[196:199], v151 offset:3072
	ds_read_b128 v[200:203], v151 offset:4096
	ds_read_b128 v[204:207], v151 offset:5120
	ds_read_b128 v[212:215], v151 offset:6144
	ds_read_b128 v[216:219], v151 offset:7168
	global_load_lds_dwordx4 v[144:145], off
	v_lshl_add_u64 v[144:145], s[20:21], 0, v[138:139]
	s_add_i32 m0, s17, 0xe000
	s_nop 0
	global_load_lds_dwordx4 v[144:145], off
	s_waitcnt vmcnt(8)
	s_waitcnt lgkmcnt(0)
	s_barrier
	s_waitcnt lgkmcnt(0)
	v_mfma_f32_16x16x32_bf16 v[124:127], v[152:155], v[184:187], 0
	v_mfma_f32_16x16x32_bf16 v[120:123], v[160:163], v[184:187], 0
	v_mfma_f32_16x16x32_bf16 v[116:119], v[152:155], v[192:195], 0
	v_mfma_f32_16x16x32_bf16 v[108:111], v[160:163], v[192:195], 0
	v_mfma_f32_16x16x32_bf16 v[100:103], v[152:155], v[200:203], 0
	v_mfma_f32_16x16x32_bf16 v[92:95], v[160:163], v[200:203], 0
	v_mfma_f32_16x16x32_bf16 v[84:87], v[152:155], v[212:215], 0
	v_mfma_f32_16x16x32_bf16 v[76:79], v[160:163], v[212:215], 0
	v_mfma_f32_16x16x32_bf16 v[124:127], v[156:159], v[188:191], v[124:127]
	v_mfma_f32_16x16x32_bf16 v[120:123], v[164:167], v[188:191], v[120:123]
	v_mfma_f32_16x16x32_bf16 v[116:119], v[156:159], v[196:199], v[116:119]
	v_mfma_f32_16x16x32_bf16 v[108:111], v[164:167], v[196:199], v[108:111]
	v_mfma_f32_16x16x32_bf16 v[100:103], v[156:159], v[204:207], v[100:103]
	v_mfma_f32_16x16x32_bf16 v[92:95], v[164:167], v[204:207], v[92:95]
	v_mfma_f32_16x16x32_bf16 v[84:87], v[156:159], v[216:219], v[84:87]
	v_mfma_f32_16x16x32_bf16 v[76:79], v[164:167], v[216:219], v[76:79]
	v_mfma_f32_16x16x32_bf16 v[112:115], v[168:171], v[184:187], 0
	v_mfma_f32_16x16x32_bf16 v[104:107], v[176:179], v[184:187], 0
	v_mfma_f32_16x16x32_bf16 v[96:99], v[168:171], v[192:195], 0
	v_mfma_f32_16x16x32_bf16 v[88:91], v[176:179], v[192:195], 0
	v_mfma_f32_16x16x32_bf16 v[80:83], v[168:171], v[200:203], 0
	v_mfma_f32_16x16x32_bf16 v[72:75], v[176:179], v[200:203], 0
	v_mfma_f32_16x16x32_bf16 v[68:71], v[168:171], v[212:215], 0
	v_mfma_f32_16x16x32_bf16 v[64:67], v[176:179], v[212:215], 0
	v_mfma_f32_16x16x32_bf16 v[112:115], v[172:175], v[188:191], v[112:115]
	v_mfma_f32_16x16x32_bf16 v[104:107], v[180:183], v[188:191], v[104:107]
	v_mfma_f32_16x16x32_bf16 v[96:99], v[172:175], v[196:199], v[96:99]
	v_mfma_f32_16x16x32_bf16 v[88:91], v[180:183], v[196:199], v[88:91]
	v_mfma_f32_16x16x32_bf16 v[80:83], v[172:175], v[204:207], v[80:83]
	v_mfma_f32_16x16x32_bf16 v[72:75], v[180:183], v[204:207], v[72:75]
	v_mfma_f32_16x16x32_bf16 v[68:71], v[172:175], v[216:219], v[68:71]
	v_mfma_f32_16x16x32_bf16 v[64:67], v[180:183], v[216:219], v[64:67]
	s_barrier
	s_add_i32 s48, s39, s26
	v_lshl_add_u64 v[144:145], s[22:23], 0, v[132:133]
	s_mov_b32 m0, s48
	ds_read_b128 v[184:187], v151 offset:16384
	ds_read_b128 v[188:191], v151 offset:17408
	ds_read_b128 v[192:195], v151 offset:18432
	ds_read_b128 v[196:199], v151 offset:19456
	ds_read_b128 v[200:203], v151 offset:20480
	ds_read_b128 v[204:207], v151 offset:21504
	ds_read_b128 v[212:215], v151 offset:22528
	ds_read_b128 v[216:219], v151 offset:23552
	global_load_lds_dwordx4 v[144:145], off
	s_add_i32 m0, s48, 0x2000
	s_add_u32 s48, s22, 0x40000
	v_lshl_add_u64 v[220:221], s[22:23], 0, v[128:129]
	s_addc_u32 s49, s23, 0
	s_add_i32 s50, s40, s26
	global_load_lds_dwordx4 v[220:221], off
	v_lshl_add_u64 v[222:223], s[48:49], 0, v[132:133]
	s_mov_b32 m0, s50
	v_lshl_add_u64 v[224:225], s[24:25], 0, v[130:131]
	global_load_lds_dwordx4 v[222:223], off
	v_lshl_add_u64 v[222:223], s[48:49], 0, v[128:129]
	s_add_i32 m0, s50, 0x2000
	s_nop 0
	global_load_lds_dwordx4 v[222:223], off
	v_lshl_add_u64 v[222:223], s[24:25], 0, v[134:135]
	s_mov_b32 m0, s17
	s_nop 0
	global_load_lds_dwordx4 v[222:223], off
	s_mov_b32 m0, s29
	s_nop 0
	global_load_lds_dwordx4 v[224:225], off
	s_waitcnt vmcnt(8)
	s_waitcnt lgkmcnt(0)
	s_barrier
	s_waitcnt lgkmcnt(0)
	v_mfma_f32_16x16x32_bf16 v[60:63], v[152:155], v[184:187], 0
	v_mfma_f32_16x16x32_bf16 v[56:59], v[160:163], v[184:187], 0
	v_mfma_f32_16x16x32_bf16 v[52:55], v[152:155], v[192:195], 0
	v_mfma_f32_16x16x32_bf16 v[44:47], v[160:163], v[192:195], 0
	v_mfma_f32_16x16x32_bf16 v[36:39], v[152:155], v[200:203], 0
	v_mfma_f32_16x16x32_bf16 v[28:31], v[160:163], v[200:203], 0
	v_mfma_f32_16x16x32_bf16 v[20:23], v[152:155], v[212:215], 0
	v_mfma_f32_16x16x32_bf16 v[12:15], v[160:163], v[212:215], 0
	v_mfma_f32_16x16x32_bf16 v[60:63], v[156:159], v[188:191], v[60:63]
	v_mfma_f32_16x16x32_bf16 v[56:59], v[164:167], v[188:191], v[56:59]
	v_mfma_f32_16x16x32_bf16 v[52:55], v[156:159], v[196:199], v[52:55]
	v_mfma_f32_16x16x32_bf16 v[44:47], v[164:167], v[196:199], v[44:47]
	v_mfma_f32_16x16x32_bf16 v[36:39], v[156:159], v[204:207], v[36:39]
	v_mfma_f32_16x16x32_bf16 v[28:31], v[164:167], v[204:207], v[28:31]
	v_mfma_f32_16x16x32_bf16 v[20:23], v[156:159], v[216:219], v[20:23]
	v_mfma_f32_16x16x32_bf16 v[12:15], v[164:167], v[216:219], v[12:15]
	v_mfma_f32_16x16x32_bf16 v[48:51], v[168:171], v[184:187], 0
	v_mfma_f32_16x16x32_bf16 v[40:43], v[176:179], v[184:187], 0
	v_mfma_f32_16x16x32_bf16 v[32:35], v[168:171], v[192:195], 0
	v_mfma_f32_16x16x32_bf16 v[24:27], v[176:179], v[192:195], 0
	v_mfma_f32_16x16x32_bf16 v[16:19], v[168:171], v[200:203], 0
	v_mfma_f32_16x16x32_bf16 v[8:11], v[176:179], v[200:203], 0
	v_mfma_f32_16x16x32_bf16 v[4:7], v[168:171], v[212:215], 0
	v_mfma_f32_16x16x32_bf16 v[0:3], v[176:179], v[212:215], 0
	v_mfma_f32_16x16x32_bf16 v[48:51], v[172:175], v[188:191], v[48:51]
	v_mfma_f32_16x16x32_bf16 v[40:43], v[180:183], v[188:191], v[40:43]
	v_mfma_f32_16x16x32_bf16 v[32:35], v[172:175], v[196:199], v[32:35]
	v_mfma_f32_16x16x32_bf16 v[24:27], v[180:183], v[196:199], v[24:27]
	v_mfma_f32_16x16x32_bf16 v[16:19], v[172:175], v[204:207], v[16:19]
	v_mfma_f32_16x16x32_bf16 v[8:11], v[180:183], v[204:207], v[8:11]
	v_mfma_f32_16x16x32_bf16 v[4:7], v[172:175], v[216:219], v[4:7]
	v_mfma_f32_16x16x32_bf16 v[0:3], v[180:183], v[216:219], v[0:3]
	s_barrier
; #define PG8_STAGE(bufoff, gbase, voff) do { _Pragma("unroll") for (int _i = 0; _i < 2; ++_i) \
;         __builtin_amdgcn_global_load_lds((const unsigned*)((const char*)(gbase) + (voff)[_i]), (PG8_LAS unsigned*)(lds + (bufoff) + ldsw + _i * 8192), 16, 0, 0); } while (0)
; #define PG8_LDA(dst, b, h) do { _Pragma("unroll") for (int m = 0; m < 4; ++m) _Pragma("unroll") for (int k = 0; k < 2; ++k) dst[m][k] = *(const PG8_LAS bf16x8*)(lds + PG8_SA(b, h) + aoff + m * 2048 + k * 1024); } while (0)
; #define PG8_LDB(dst, b, h) do { _Pragma("unroll") for (int n = 0; n < 2; ++n) _Pragma("unroll") for (int k = 0; k < 2; ++k) dst[n][k] = *(const PG8_LAS bf16x8*)(lds + PG8_SB(b, h) + boff + n * 2048 + k * 1024); } while (0)
; #define PG8_MMA(ai, bj, At, Bt) do { __builtin_amdgcn_s_setprio(1); _Pragma("unroll") for (int m = 0; m < 4; ++m) _Pragma("unroll") for (int n = 0; n < 2; ++n) _Pragma("unroll") for (int k = 0; k < 2; ++k) \
;         acc[ai][bj][m][n] = __builtin_amdgcn_mfma_f32_16x16x32_bf16(Bt[n][k], At[m][k], acc[ai][bj][m][n], 0, 0, 0); __builtin_amdgcn_s_setprio(0); } while (0)
; #define PG8_WAIT_V(n) asm volatile("s_waitcnt vmcnt(" #n ")" ::: "memory")
; #define PG8_WAIT_L(n) asm volatile("s_waitcnt lgkmcnt(" #n ")" ::: "memory")
; #define PG8_BAR __builtin_amdgcn_s_barrier()
; #define PG8_SCHED __builtin_amdgcn_sched_barrier(0)
; template <class Epi, class Sched, bool ALIGN_EPI = false, bool SP2 = false>
; __device__ __forceinline__ void gemm_phase(PG8_LAS unsigned char* lds, const Gemm g, const Sched& S, const Epi& E, const int wid) {
;     ...
;             PG8_LDB(B0, 1, 0); PG8_LDB(B1, 1, 1); PG8_SCHED; PG8_LDA(At, 1, 0); PG8_STAGE(PG8_SA(0, 1), a2 + hstep, voffA);
;             PG8_WAIT_V(8); PG8_WAIT_L(0); PG8_BAR; PG8_MMA(0, 0, At, B0); PG8_MMA(0, 1, At, B1); PG8_BAR; PG8_SCHED;
	s_add_i32 s48, 0, 0x18000
	s_add_i32 s49, 0, 0x1c000
	v_add_u32_e32 v164, s48, v147
	v_add_u32_e32 v180, s49, v147
	ds_read_b128 v[152:155], v164
	ds_read_b128 v[156:159], v164 offset:1024
	ds_read_b128 v[160:163], v164 offset:2048
	ds_read_b128 v[164:167], v164 offset:3072
	ds_read_b128 v[168:171], v180
	ds_read_b128 v[172:175], v180 offset:1024
	ds_read_b128 v[176:179], v180 offset:2048
	ds_read_b128 v[180:183], v180 offset:3072
	s_add_u32 s24, s24, 0x40000
	s_addc_u32 s25, s25, 0
	s_mov_b32 m0, s30
	v_lshl_add_u64 v[226:227], s[24:25], 0, v[134:135]
	ds_read_b128 v[184:187], v151 offset:32768
	ds_read_b128 v[188:191], v151 offset:33792
	ds_read_b128 v[192:195], v151 offset:34816
	ds_read_b128 v[196:199], v151 offset:35840
	ds_read_b128 v[200:203], v151 offset:36864
	ds_read_b128 v[204:207], v151 offset:37888
	ds_read_b128 v[212:215], v151 offset:38912
	ds_read_b128 v[216:219], v151 offset:39936
	global_load_lds_dwordx4 v[226:227], off
	v_lshl_add_u64 v[226:227], s[24:25], 0, v[130:131]
	s_mov_b32 m0, s31
	s_nop 0
	global_load_lds_dwordx4 v[226:227], off
	s_waitcnt vmcnt(8)
	s_waitcnt lgkmcnt(0)
	s_barrier
	s_waitcnt lgkmcnt(0)
	v_mfma_f32_16x16x32_bf16 v[124:127], v[152:155], v[184:187], v[124:127]
	v_mfma_f32_16x16x32_bf16 v[120:123], v[160:163], v[184:187], v[120:123]
	v_mfma_f32_16x16x32_bf16 v[116:119], v[152:155], v[192:195], v[116:119]
	v_mfma_f32_16x16x32_bf16 v[108:111], v[160:163], v[192:195], v[108:111]
	v_mfma_f32_16x16x32_bf16 v[100:103], v[152:155], v[200:203], v[100:103]
	v_mfma_f32_16x16x32_bf16 v[92:95], v[160:163], v[200:203], v[92:95]
	v_mfma_f32_16x16x32_bf16 v[84:87], v[152:155], v[212:215], v[84:87]
	v_mfma_f32_16x16x32_bf16 v[76:79], v[160:163], v[212:215], v[76:79]
	v_mfma_f32_16x16x32_bf16 v[124:127], v[156:159], v[188:191], v[124:127]
	v_mfma_f32_16x16x32_bf16 v[120:123], v[164:167], v[188:191], v[120:123]
	v_mfma_f32_16x16x32_bf16 v[116:119], v[156:159], v[196:199], v[116:119]
	v_mfma_f32_16x16x32_bf16 v[108:111], v[164:167], v[196:199], v[108:111]
	v_mfma_f32_16x16x32_bf16 v[100:103], v[156:159], v[204:207], v[100:103]
	v_mfma_f32_16x16x32_bf16 v[92:95], v[164:167], v[204:207], v[92:95]
	v_mfma_f32_16x16x32_bf16 v[84:87], v[156:159], v[216:219], v[84:87]
	v_mfma_f32_16x16x32_bf16 v[76:79], v[164:167], v[216:219], v[76:79]
	v_mfma_f32_16x16x32_bf16 v[112:115], v[168:171], v[184:187], v[112:115]
	v_mfma_f32_16x16x32_bf16 v[104:107], v[176:179], v[184:187], v[104:107]
	v_mfma_f32_16x16x32_bf16 v[96:99], v[168:171], v[192:195], v[96:99]
	v_mfma_f32_16x16x32_bf16 v[88:91], v[176:179], v[192:195], v[88:91]
	v_mfma_f32_16x16x32_bf16 v[80:83], v[168:171], v[200:203], v[80:83]
	v_mfma_f32_16x16x32_bf16 v[72:75], v[176:179], v[200:203], v[72:75]
	v_mfma_f32_16x16x32_bf16 v[68:71], v[168:171], v[212:215], v[68:71]
	v_mfma_f32_16x16x32_bf16 v[64:67], v[176:179], v[212:215], v[64:67]
	v_mfma_f32_16x16x32_bf16 v[112:115], v[172:175], v[188:191], v[112:115]
	v_mfma_f32_16x16x32_bf16 v[104:107], v[180:183], v[188:191], v[104:107]
	v_mfma_f32_16x16x32_bf16 v[96:99], v[172:175], v[196:199], v[96:99]
	v_mfma_f32_16x16x32_bf16 v[88:91], v[180:183], v[196:199], v[88:91]
	v_mfma_f32_16x16x32_bf16 v[80:83], v[172:175], v[204:207], v[80:83]
	v_mfma_f32_16x16x32_bf16 v[72:75], v[180:183], v[204:207], v[72:75]
	v_mfma_f32_16x16x32_bf16 v[68:71], v[172:175], v[216:219], v[68:71]
	v_mfma_f32_16x16x32_bf16 v[64:67], v[180:183], v[216:219], v[64:67]
	s_barrier
; #define PG8_STAGE(bufoff, gbase, voff) do { _Pragma("unroll") for (int _i = 0; _i < 2; ++_i) \
;         __builtin_amdgcn_global_load_lds((const unsigned*)((const char*)(gbase) + (voff)[_i]), (PG8_LAS unsigned*)(lds + (bufoff) + ldsw + _i * 8192), 16, 0, 0); } while (0)
; #define PG8_LDA(dst, b, h) do { _Pragma("unroll") for (int m = 0; m < 4; ++m) _Pragma("unroll") for (int k = 0; k < 2; ++k) dst[m][k] = *(const PG8_LAS bf16x8*)(lds + PG8_SA(b, h) + aoff + m * 2048 + k * 1024); } while (0)
; #define PG8_MMA(ai, bj, At, Bt) do { __builtin_amdgcn_s_setprio(1); _Pragma("unroll") for (int m = 0; m < 4; ++m) _Pragma("unroll") for (int n = 0; n < 2; ++n) _Pragma("unroll") for (int k = 0; k < 2; ++k) \
;         acc[ai][bj][m][n] = __builtin_amdgcn_mfma_f32_16x16x32_bf16(Bt[n][k], At[m][k], acc[ai][bj][m][n], 0, 0, 0); __builtin_amdgcn_s_setprio(0); } while (0)
; #define PG8_WAIT_V(n) asm volatile("s_waitcnt vmcnt(" #n ")" ::: "memory")
; #define PG8_WAIT_L(n) asm volatile("s_waitcnt lgkmcnt(" #n ")" ::: "memory")
; #define PG8_BAR __builtin_amdgcn_s_barrier()
; #define PG8_SCHED __builtin_amdgcn_sched_barrier(0)
; template <class Epi, class Sched, bool ALIGN_EPI = false, bool SP2 = false>
; __device__ __forceinline__ void gemm_phase(PG8_LAS unsigned char* lds, const Gemm g, const Sched& S, const Epi& E, const int wid) {
;     ...
;             PG8_LDA(At, 1, 1); PG8_STAGE(PG8_SB(1, 0), b3, voffB); PG8_STAGE(PG8_SB(1, 1), b3 + hstep, voffB); PG8_STAGE(PG8_SA(1, 0), a3, voffA);
;             PG8_WAIT_V(8); PG8_WAIT_L(0); PG8_BAR; PG8_MMA(1, 0, At, B0); PG8_MMA(1, 1, At, B1); PG8_BAR; PG8_SCHED;
	s_add_i32 s24, s48, s26
	v_lshl_add_u64 v[144:145], v[144:145], 0, s[6:7]
	s_mov_b32 m0, s24
	ds_read_b128 v[184:187], v151 offset:49152
	ds_read_b128 v[188:191], v151 offset:50176
	ds_read_b128 v[192:195], v151 offset:51200
	ds_read_b128 v[196:199], v151 offset:52224
	ds_read_b128 v[200:203], v151 offset:53248
	ds_read_b128 v[204:207], v151 offset:54272
	ds_read_b128 v[212:215], v151 offset:55296
	ds_read_b128 v[216:219], v151 offset:56320
	global_load_lds_dwordx4 v[144:145], off
	s_add_i32 m0, s24, 0x2000
	s_add_u32 s22, s22, 0x40080
	v_lshl_add_u64 v[144:145], v[220:221], 0, s[6:7]
	s_addc_u32 s23, s23, 0
	s_add_i32 s24, s49, s26
	global_load_lds_dwordx4 v[144:145], off
	v_lshl_add_u64 v[144:145], s[22:23], 0, v[132:133]
	s_mov_b32 m0, s24
	s_nop 0
	global_load_lds_dwordx4 v[144:145], off
	v_lshl_add_u64 v[144:145], s[22:23], 0, v[128:129]
	s_add_i32 m0, s24, 0x2000
	s_nop 0
	global_load_lds_dwordx4 v[144:145], off
	v_lshl_add_u64 v[144:145], v[222:223], 0, s[6:7]
	s_mov_b32 m0, s37
	s_nop 0
	global_load_lds_dwordx4 v[144:145], off
	v_lshl_add_u64 v[144:145], v[224:225], 0, s[6:7]
	s_mov_b32 m0, s38
	s_nop 0
	global_load_lds_dwordx4 v[144:145], off
	s_waitcnt vmcnt(8)
	s_waitcnt lgkmcnt(0)
	s_barrier
	s_waitcnt lgkmcnt(0)
	v_mfma_f32_16x16x32_bf16 v[60:63], v[152:155], v[184:187], v[60:63]
	v_mfma_f32_16x16x32_bf16 v[56:59], v[160:163], v[184:187], v[56:59]
	v_mfma_f32_16x16x32_bf16 v[52:55], v[152:155], v[192:195], v[52:55]
	v_mfma_f32_16x16x32_bf16 v[44:47], v[160:163], v[192:195], v[44:47]
	v_mfma_f32_16x16x32_bf16 v[36:39], v[152:155], v[200:203], v[36:39]
	v_mfma_f32_16x16x32_bf16 v[28:31], v[160:163], v[200:203], v[28:31]
	v_mfma_f32_16x16x32_bf16 v[20:23], v[152:155], v[212:215], v[20:23]
	v_mfma_f32_16x16x32_bf16 v[12:15], v[160:163], v[212:215], v[12:15]
	v_mfma_f32_16x16x32_bf16 v[60:63], v[156:159], v[188:191], v[60:63]
	v_mfma_f32_16x16x32_bf16 v[56:59], v[164:167], v[188:191], v[56:59]
	v_mfma_f32_16x16x32_bf16 v[52:55], v[156:159], v[196:199], v[52:55]
	v_mfma_f32_16x16x32_bf16 v[44:47], v[164:167], v[196:199], v[44:47]
	v_mfma_f32_16x16x32_bf16 v[36:39], v[156:159], v[204:207], v[36:39]
	v_mfma_f32_16x16x32_bf16 v[28:31], v[164:167], v[204:207], v[28:31]
	v_mfma_f32_16x16x32_bf16 v[20:23], v[156:159], v[216:219], v[20:23]
	v_mfma_f32_16x16x32_bf16 v[12:15], v[164:167], v[216:219], v[12:15]
	v_mfma_f32_16x16x32_bf16 v[48:51], v[168:171], v[184:187], v[48:51]
	v_mfma_f32_16x16x32_bf16 v[40:43], v[176:179], v[184:187], v[40:43]
	v_mfma_f32_16x16x32_bf16 v[32:35], v[168:171], v[192:195], v[32:35]
	v_mfma_f32_16x16x32_bf16 v[24:27], v[176:179], v[192:195], v[24:27]
	v_mfma_f32_16x16x32_bf16 v[16:19], v[168:171], v[200:203], v[16:19]
	v_mfma_f32_16x16x32_bf16 v[8:11], v[176:179], v[200:203], v[8:11]
	v_mfma_f32_16x16x32_bf16 v[4:7], v[168:171], v[212:215], v[4:7]
	v_mfma_f32_16x16x32_bf16 v[0:3], v[176:179], v[212:215], v[0:3]
	v_mfma_f32_16x16x32_bf16 v[48:51], v[172:175], v[188:191], v[48:51]
	v_mfma_f32_16x16x32_bf16 v[40:43], v[180:183], v[188:191], v[40:43]
	v_mfma_f32_16x16x32_bf16 v[32:35], v[172:175], v[196:199], v[32:35]
	v_mfma_f32_16x16x32_bf16 v[24:27], v[180:183], v[196:199], v[24:27]
	v_mfma_f32_16x16x32_bf16 v[16:19], v[172:175], v[204:207], v[16:19]
	v_mfma_f32_16x16x32_bf16 v[8:11], v[180:183], v[204:207], v[8:11]
	v_mfma_f32_16x16x32_bf16 v[4:7], v[172:175], v[216:219], v[4:7]
	v_mfma_f32_16x16x32_bf16 v[0:3], v[180:183], v[216:219], v[0:3]
	s_barrier
	s_add_i32 s47, s47, 2
	s_add_u32 s20, s20, 0x100
	s_addc_u32 s21, s21, 0
	s_add_u32 s45, s45, 0x100
	s_addc_u32 s46, s46, 0
	s_cmp_gt_u32 s47, 13
	s_cbranch_scc0 .LBB0_882
	s_branch .Lkp_exit_2
	.p2align 6

; #define WAIT_BAR(N) asm volatile("s_waitcnt vmcnt(" #N ") lgkmcnt(0)\n\ts_barrier":::"memory")
;   #define DMA_K(t,slot) glds16(ksrc+(long)(t)*KVBLK*PD,(unsigned)__builtin_amdgcn_readfirstlane(kdst+(slot)))
;   #define DMA_V(t,slot) glds16(vsrc+(long)(t)*KVBLK*PD,(unsigned)__builtin_amdgcn_readfirstlane(vdst+(slot)))
;   #define CMASK(P0,P1,t) do{int jb_=(t)-(NT-4); if(jb_>=0)cmask(P0,P1,jb_,qrel,hi);}while(0)
;   #define START(P0,P1) do{ const float rm=rowmax(P0,P1); resc=false; \
;     { const float dl=rm; mhat=fadd_s(mhat,dl); \
;       _Pragma("unroll") for(int r=0;r<16;++r){P0[r]=fsub_s(P0[r],dl);P1[r]=fsub_s(P1[r],dl);} \
;       _Pragma("unroll") for(int r=0;r<16;++r)negm[r]=-mhat; asm volatile("":"+v"(negm)); } \
;     _Pragma("unroll") for(int r=0;r<16;++r)P0[r]=__builtin_amdgcn_exp2f(P0[r]); }while(0)
;   #define ROT() do{sl_prev=sl_cur;sl_cur=sl_next;sl_next=(sl_next==(NSLOT-1)*SLOTB)?0:sl_next+SLOTB;}while(0)
;   #define CMASK(P0,P1,t) do{}while(0)
;   #define CMASK(P0,P1,t) do{int jb_=(t)-(NT-4); if(jb_>=0)cmask(P0,P1,jb_,qrel,hi);}while(0)
; template<int THRL> __device__ __forceinline__ void attn_unit(int b,int h,int qb,const bf16*Q,const bf16*__restrict__ K,const bf16*__restrict__ V,bf16*O,char*shm,const int wid){
;     ...
;   qkt(pA0,pA1,Kbase,qr,negm,r32,hi);asm volatile("s_nop 15\n\ts_nop 7":"+v"(pA0),"+v"(pA1));CMASK(pA0,pA1,0);
;   START(pA0,pA1);
;   _Pragma("unroll") for(int r=0;r<16;++r)pA1[r]=__builtin_amdgcn_exp2f(pA1[r]);
;   WAIT_BAR(0);
;   DMA_K(3,0);DMA_V(1,SLOTB);
;   ROT();
;   kload8(kf,kp0+sl_cur);
;   WAIT_BAR(2);
;   s16x4 vlo[8],vhi[8]; u32x4 pw0,pw1,pw2,pw3;
.LBB0_1545:
	v_lshlrev_b32_e32 v0, 1, v210
	v_and_b32_e32 v217, 32, v0
	v_lshlrev_b32_e32 v0, 4, v210
	v_and_b32_e32 v0, 0xc0, v0
	v_lshl_or_b32 v215, v213, 8, v0
	v_add_u32_e32 v0, 0, v217
	v_add3_u32 v221, v0, v214, v215
	v_max3_f32 v0, v18, v19, v2
	v_max3_f32 v36, v20, v21, v3
	s_sub_i32 s3, 0x1000, s36
	v_max3_f32 v0, v0, v4, v5
	v_max3_f32 v36, v36, v24, v25
	s_lshr_b32 s3, s3, 6
	v_max3_f32 v0, v0, v22, v23
	v_max3_f32 v36, v36, v8, v9
	s_cmp_lg_u32 0, -1
	v_max3_f32 v0, v0, v6, v7
	v_max3_f32 v36, v36, v28, v29
	v_lshl_add_u64 v[198:199], v[34:35], 0, s[22:23]
	v_max3_f32 v0, v0, v26, v27
	v_max3_f32 v36, v36, v12, v13
	s_mov_b32 s8, 1
	v_max3_f32 v0, v0, v10, v11
	v_max3_f32 v36, v36, v32, v33
	s_mov_b32 s38, 0
	v_max3_f32 v0, v0, v30, v31
	v_max3_f32 v36, v36, v16, v17
	v_lshlrev_b32_e32 v222, 4, v213
	v_max3_f32 v0, v0, v14, v15
	s_nop 0
	v_max_f32_e32 v0, v0, v36
	s_nop 0
	v_mov_b32_e32 v36, v0
	s_nop 1
	v_permlane32_swap_b32_e32 v0, v36
	v_max_f32_e32 v0, v0, v36
	s_nop 0
	v_add_f32_e32 v219, v1, v0
	v_sub_f32_e32 v2, v2, v0
	v_sub_f32_e32 v3, v3, v0
	v_sub_f32_e32 v18, v18, v0
	v_sub_f32_e32 v19, v19, v0
	v_sub_f32_e32 v20, v20, v0
	s_nop 0
	v_xor_b32_e32 v48, 0x80000000, v219
	v_mov_b32_e32 v49, v48
	v_mov_b32_e32 v50, v48
	v_mov_b32_e32 v51, v48
	v_mov_b32_e32 v52, v48
	v_mov_b32_e32 v53, v48
	v_mov_b32_e32 v54, v48
	v_mov_b32_e32 v55, v48
	v_mov_b32_e32 v56, v48
	v_mov_b32_e32 v57, v48
	v_mov_b32_e32 v58, v48
	v_mov_b32_e32 v59, v48
	v_mov_b32_e32 v60, v48
	v_mov_b32_e32 v61, v48
	v_mov_b32_e32 v62, v48
	v_mov_b32_e32 v63, v48
	s_waitcnt vmcnt(0) lgkmcnt(0)
	s_barrier
	v_exp_f32_e32 v64, v2
	v_exp_f32_e32 v65, v3
	v_lshl_add_u64 v[2:3], v[196:197], 0, s[20:21]
	s_mov_b32 s9, m0
	s_mov_b32 m0, s46
	s_nop 0
	global_load_lds_dwordx4 v[2:3], off
	s_mov_b32 m0, s9
	s_cselect_b32 s9, 0, 0
	s_add_i32 s9, s9, s45
	s_add_i32 s9, s9, 0x8000
	s_mov_b32 s13, m0
	s_mov_b32 m0, s9
	s_nop 0
	global_load_lds_dwordx4 v[198:199], off
	s_mov_b32 m0, s13
	ds_read_b128 v[188:191], v220 offset:8192
	ds_read_b128 v[184:187], v220 offset:8704
	ds_read_b128 v[180:183], v220 offset:10240
	ds_read_b128 v[176:179], v220 offset:10752
	ds_read_b128 v[172:175], v220 offset:12288
	ds_read_b128 v[168:171], v220 offset:12800
	ds_read_b128 v[164:167], v220 offset:14336
	ds_read_b128 v[160:163], v220 offset:14848
	v_sub_f32_e32 v4, v4, v0
	v_sub_f32_e32 v21, v21, v0
	v_sub_f32_e32 v5, v5, v0
	v_sub_f32_e32 v22, v22, v0
	v_sub_f32_e32 v6, v6, v0
	v_sub_f32_e32 v23, v23, v0
	v_sub_f32_e32 v7, v7, v0
	v_sub_f32_e32 v24, v24, v0
	v_sub_f32_e32 v8, v8, v0
	v_sub_f32_e32 v25, v25, v0
	v_sub_f32_e32 v9, v9, v0
	v_sub_f32_e32 v26, v26, v0
	v_sub_f32_e32 v10, v10, v0
	v_sub_f32_e32 v27, v27, v0
	v_sub_f32_e32 v11, v11, v0
	v_sub_f32_e32 v28, v28, v0
	v_sub_f32_e32 v12, v12, v0
	v_sub_f32_e32 v29, v29, v0
	v_sub_f32_e32 v13, v13, v0
	v_sub_f32_e32 v30, v30, v0
	v_sub_f32_e32 v14, v14, v0
	v_sub_f32_e32 v31, v31, v0
	v_sub_f32_e32 v15, v15, v0
	v_sub_f32_e32 v32, v32, v0
	v_sub_f32_e32 v16, v16, v0
	v_sub_f32_e32 v33, v33, v0
	v_sub_f32_e32 v0, v17, v0
	v_exp_f32_e32 v80, v18
	v_exp_f32_e32 v81, v19
	v_exp_f32_e32 v82, v20
	v_exp_f32_e32 v83, v21
	v_exp_f32_e32 v84, v22
	v_exp_f32_e32 v85, v23
	v_exp_f32_e32 v86, v24
	v_exp_f32_e32 v87, v25
	v_exp_f32_e32 v88, v26
	v_exp_f32_e32 v89, v27
	v_exp_f32_e32 v90, v28
	v_exp_f32_e32 v91, v29
	v_exp_f32_e32 v92, v30
	v_exp_f32_e32 v93, v31
	v_exp_f32_e32 v94, v32
	v_exp_f32_e32 v95, v33
	v_exp_f32_e32 v66, v4
	v_exp_f32_e32 v67, v5
	v_exp_f32_e32 v68, v6
	v_exp_f32_e32 v69, v7
	v_exp_f32_e32 v70, v8
	v_exp_f32_e32 v71, v9
	v_exp_f32_e32 v72, v10
	v_exp_f32_e32 v73, v11
	v_exp_f32_e32 v74, v12
	v_exp_f32_e32 v75, v13
	v_exp_f32_e32 v76, v14
	v_exp_f32_e32 v77, v15
	v_exp_f32_e32 v78, v16
	v_exp_f32_e32 v79, v0
	s_waitcnt vmcnt(2) lgkmcnt(0)
	s_barrier
	s_andn2_b64 vcc, exec, s[6:7]
	v_cmp_gt_u32_e64 s[6:7], 32, v210
	s_cbranch_vccnz .LBB0_1561
	v_mov_b32_e32 v14, v1
	v_mov_b32_e32 v15, v1
	v_lshl_add_u64 v[200:201], v[34:35], 0, s[20:21]
	v_mov_b32_e32 v0, v1
	v_mov_b32_e32 v2, v1
	v_mov_b32_e32 v3, v1
	v_mov_b32_e32 v4, v1
	v_mov_b32_e32 v5, v1
	v_mov_b32_e32 v6, v1
	v_mov_b32_e32 v7, v1
	v_mov_b32_e32 v8, v1
	v_mov_b32_e32 v9, v1
	v_mov_b32_e32 v10, v1
	v_mov_b32_e32 v11, v1
	v_mov_b32_e32 v12, v1
	v_mov_b32_e32 v13, v1
	v_mov_b64_e32 v[46:47], v[14:15]
	v_mov_b64_e32 v[30:31], v[14:15]
	v_lshl_add_u32 v204, v212, 2, s48
	v_lshl_add_u64 v[202:203], v[196:197], 0, s[24:25]
	s_mov_b32 s8, 0
	s_movk_i32 s38, 0x4000
	s_movk_i32 s40, 0x2000
	v_mov_b32_e32 v223, 0
	s_mov_b32 s39, 6
	v_mov_b64_e32 v[44:45], v[12:13]
	v_mov_b64_e32 v[42:43], v[10:11]
	v_mov_b64_e32 v[40:41], v[8:9]
	v_mov_b64_e32 v[38:39], v[6:7]
	v_mov_b64_e32 v[36:37], v[4:5]
	v_mov_b64_e32 v[34:35], v[2:3]
	v_mov_b64_e32 v[32:33], v[0:1]
	v_mov_b64_e32 v[28:29], v[12:13]
	v_mov_b64_e32 v[26:27], v[10:11]
	v_mov_b64_e32 v[24:25], v[8:9]
	v_mov_b64_e32 v[22:23], v[6:7]
	v_mov_b64_e32 v[20:21], v[4:5]
	v_mov_b64_e32 v[18:19], v[2:3]
	v_mov_b64_e32 v[16:17], v[0:1]
	.p2align 6

; template <class Epi, class Sched, bool ALIGN_EPI = false, bool SP2 = false>
; __device__ __forceinline__ void gemm_phase(PG8_LAS unsigned char* lds, const Gemm g, const Sched& S, const Epi& E, const int wid) {
;     ...
;         const bool has_next = S.next(ui + 1, nxt);
;         const char* nA = has_next ? (const char*)g.A + (size_t)nxt.pm * tstep : cA; const char* nB = has_next ? (const char*)g.Bt + (size_t)nxt.pn * tstep : cB;
;         for (int t = 0; t < nt; t += 2) {
;             const bool last = (t == nt - 2);
;             const char* a1 = cA + (size_t)(t + 1) * kstep;
;             const char* a2 = last ? nA : cA + (size_t)(t + 2) * kstep; const char* b2 = last ? nB : cB + (size_t)(t + 2) * kstep;
;             const char* a3 = a2 + kstep; const char* b3 = b2 + kstep;
.LBB0_1785:
	s_add_u32 s44, s20, 0x100
	s_addc_u32 s45, s21, 0
	s_ashr_i32 s15, s14, 31
	s_lshl_b64 s[16:17], s[14:15], 19
	s_add_u32 s18, s27, s16
	s_addc_u32 s19, s28, s17
	s_and_b64 s[16:17], s[6:7], exec
	s_cselect_b32 s15, s19, s9
	s_cselect_b32 s46, s18, s8
	s_ashr_i32 s13, s12, 31
	s_lshl_b64 s[16:17], s[12:13], 19
	s_add_u32 s16, s29, s16
	s_addc_u32 s17, s30, s17
	s_and_b64 s[22:23], s[6:7], exec
	s_cselect_b32 s13, s17, s21
	s_cselect_b32 s47, s16, s20
	v_lshl_add_u64 v[144:145], s[8:9], 0, v[136:137]
	v_lshl_add_u64 v[146:147], s[8:9], 0, v[138:139]
	s_mov_b32 s48, -2
	s_mov_b64 s[20:21], 0
	.p2align 6

; template <class Epi, class Sched, bool ALIGN_EPI = false, bool SP2 = false>
; __device__ __forceinline__ void gemm_phase(PG8_LAS unsigned char* lds, const Gemm g, const Sched& S, const Epi& E, const int wid) {
;     ...
;         const bool has_next = S.next(ui + 1, nxt);
;         const char* nA = has_next ? (const char*)g.A + (size_t)nxt.pm * tstep : cA; const char* nB = has_next ? (const char*)g.Bt + (size_t)nxt.pn * tstep : cB;
.LBB0_1911:
	s_ashr_i32 s15, s14, 31
	s_lshl_b64 s[16:17], s[14:15], 19
	s_add_u32 s16, s80, s16
	s_addc_u32 s17, s81, s17
	s_and_b64 s[18:19], s[4:5], exec
	s_cselect_b32 s15, s17, s23
	s_cselect_b32 s42, s16, s22
	s_ashr_i32 s13, s12, 31
	s_lshl_b64 s[18:19], s[12:13], 19
	s_add_u32 s18, s10, s18
	s_addc_u32 s19, s11, s19
	s_and_b64 s[26:27], s[4:5], exec
	s_cselect_b32 s13, s19, s25
	s_cselect_b32 s43, s18, s24
	s_add_u32 s22, s22, 0x40080
	s_addc_u32 s23, s23, 0
	s_add_u32 s44, s24, 0x100

; template <class Epi, class Sched, bool ALIGN_EPI = false, bool SP2 = false>
; __device__ __forceinline__ void gemm_phase(PG8_LAS unsigned char* lds, const Gemm g, const Sched& S, const Epi& E, const int wid) {
;     ...
;         const char* nA = has_next ? (const char*)g.A + (size_t)nxt.pm * tstep : cA; const char* nB = has_next ? (const char*)g.Bt + (size_t)nxt.pn * tstep : cB;
;         for (int t = 0; t < nt; t += 2) {
	s_addc_u32 s45, s25, 0
	s_mov_b32 s46, -2


; #define PG8_STAGE(bufoff, gbase, voff) do { _Pragma("unroll") for (int _i = 0; _i < 2; ++_i) \
;         __builtin_amdgcn_global_load_lds((const unsigned*)((const char*)(gbase) + (voff)[_i]), (PG8_LAS unsigned*)(lds + (bufoff) + ldsw + _i * 8192), 16, 0, 0); } while (0)
; #define PG8_LDA(dst, b, h) do { _Pragma("unroll") for (int m = 0; m < 4; ++m) _Pragma("unroll") for (int k = 0; k < 2; ++k) dst[m][k] = *(const PG8_LAS bf16x8*)(lds + PG8_SA(b, h) + aoff + m * 2048 + k * 1024); } while (0)
; #define PG8_LDB(dst, b, h) do { _Pragma("unroll") for (int n = 0; n < 2; ++n) _Pragma("unroll") for (int k = 0; k < 2; ++k) dst[n][k] = *(const PG8_LAS bf16x8*)(lds + PG8_SB(b, h) + boff + n * 2048 + k * 1024); } while (0)
; #define PG8_MMA(ai, bj, At, Bt) do { __builtin_amdgcn_s_setprio(1); _Pragma("unroll") for (int m = 0; m < 4; ++m) _Pragma("unroll") for (int n = 0; n < 2; ++n) _Pragma("unroll") for (int k = 0; k < 2; ++k) \
;         acc[ai][bj][m][n] = __builtin_amdgcn_mfma_f32_16x16x32_bf16(Bt[n][k], At[m][k], acc[ai][bj][m][n], 0, 0, 0); __builtin_amdgcn_s_setprio(0); } while (0)
; #define PG8_WAIT_V(n) asm volatile("s_waitcnt vmcnt(" #n ")" ::: "memory")
; #define PG8_WAIT_L(n) asm volatile("s_waitcnt lgkmcnt(" #n ")" ::: "memory")
; #define PG8_BAR __builtin_amdgcn_s_barrier()
; #define PG8_SCHED __builtin_amdgcn_sched_barrier(0)
; template <class Epi, class Sched, bool ALIGN_EPI = false, bool SP2 = false>
; __device__ __forceinline__ void gemm_phase(PG8_LAS unsigned char* lds, const Gemm g, const Sched& S, const Epi& E, const int wid) {
;     ...
;             PG8_LDB(B0, 0, 0); PG8_LDB(B1, 0, 1); PG8_SCHED; PG8_LDA(At, 0, 0); PG8_STAGE(PG8_SA(1, 1), a1 + hstep, voffA);
;             PG8_WAIT_V(8); PG8_WAIT_L(0); PG8_BAR; PG8_MMA(0, 0, At, B0); PG8_MMA(0, 1, At, B1); PG8_BAR; PG8_SCHED;
;             PG8_LDA(At, 0, 1); PG8_STAGE(PG8_SB(0, 0), b2, voffB); PG8_STAGE(PG8_SB(0, 1), b2 + hstep, voffB); PG8_STAGE(PG8_SA(0, 0), a2, voffA);
;             PG8_WAIT_V(8); PG8_WAIT_L(0); PG8_BAR; PG8_MMA(1, 0, At, B0); PG8_MMA(1, 1, At, B1); PG8_BAR; PG8_SCHED;
	ds_read_b128 v[144:147], v151
	ds_read_b128 v[154:157], v151 offset:1024
	ds_read_b128 v[158:161], v151 offset:2048
	ds_read_b128 v[162:165], v151 offset:3072
	ds_read_b128 v[166:169], v152
	ds_read_b128 v[170:173], v152 offset:1024
	ds_read_b128 v[174:177], v152 offset:2048
	ds_read_b128 v[178:181], v152 offset:3072
	s_add_u32 s24, s22, 0xfffc0080
	s_addc_u32 s25, s23, -1
	s_cmp_eq_u32 s46, 12
	s_cselect_b32 s27, s15, s25
	s_cselect_b32 s26, s42, s24
	s_cselect_b32 s25, s13, s45
	s_cselect_b32 s24, s43, s44
	v_lshl_add_u64 v[206:207], s[22:23], 0, v[136:137]
	s_add_i32 m0, s21, 0xc000
	ds_read_b128 v[182:185], v153
	ds_read_b128 v[186:189], v153 offset:1024
	ds_read_b128 v[190:193], v153 offset:2048
	ds_read_b128 v[194:197], v153 offset:3072
	ds_read_b128 v[198:201], v153 offset:4096
	ds_read_b128 v[202:205], v153 offset:5120
	ds_read_b128 v[210:213], v153 offset:6144
	ds_read_b128 v[214:217], v153 offset:7168
	global_load_lds_dwordx4 v[206:207], off
	v_lshl_add_u64 v[206:207], s[22:23], 0, v[138:139]
	s_add_i32 m0, s21, 0xe000
	s_nop 0
	global_load_lds_dwordx4 v[206:207], off
	s_waitcnt vmcnt(8)
	s_waitcnt lgkmcnt(0)
	s_barrier
	s_waitcnt lgkmcnt(0)
	v_mfma_f32_16x16x32_bf16 v[124:127], v[144:147], v[182:185], 0
	v_mfma_f32_16x16x32_bf16 v[116:119], v[158:161], v[182:185], 0
	v_mfma_f32_16x16x32_bf16 v[108:111], v[144:147], v[190:193], 0
	v_mfma_f32_16x16x32_bf16 v[100:103], v[158:161], v[190:193], 0
	v_mfma_f32_16x16x32_bf16 v[92:95], v[144:147], v[198:201], 0
	v_mfma_f32_16x16x32_bf16 v[84:87], v[158:161], v[198:201], 0
	v_mfma_f32_16x16x32_bf16 v[76:79], v[144:147], v[210:213], 0
	v_mfma_f32_16x16x32_bf16 v[68:71], v[158:161], v[210:213], 0
	v_mfma_f32_16x16x32_bf16 v[124:127], v[154:157], v[186:189], v[124:127]
	v_mfma_f32_16x16x32_bf16 v[116:119], v[162:165], v[186:189], v[116:119]
	v_mfma_f32_16x16x32_bf16 v[108:111], v[154:157], v[194:197], v[108:111]
	v_mfma_f32_16x16x32_bf16 v[100:103], v[162:165], v[194:197], v[100:103]
	v_mfma_f32_16x16x32_bf16 v[92:95], v[154:157], v[202:205], v[92:95]
	v_mfma_f32_16x16x32_bf16 v[84:87], v[162:165], v[202:205], v[84:87]
	v_mfma_f32_16x16x32_bf16 v[76:79], v[154:157], v[214:217], v[76:79]
	v_mfma_f32_16x16x32_bf16 v[68:71], v[162:165], v[214:217], v[68:71]
	v_mfma_f32_16x16x32_bf16 v[120:123], v[166:169], v[182:185], 0
	v_mfma_f32_16x16x32_bf16 v[112:115], v[174:177], v[182:185], 0
	v_mfma_f32_16x16x32_bf16 v[104:107], v[166:169], v[190:193], 0
	v_mfma_f32_16x16x32_bf16 v[96:99], v[174:177], v[190:193], 0
	v_mfma_f32_16x16x32_bf16 v[88:91], v[166:169], v[198:201], 0
	v_mfma_f32_16x16x32_bf16 v[80:83], v[174:177], v[198:201], 0
	v_mfma_f32_16x16x32_bf16 v[72:75], v[166:169], v[210:213], 0
	v_mfma_f32_16x16x32_bf16 v[64:67], v[174:177], v[210:213], 0
	v_mfma_f32_16x16x32_bf16 v[120:123], v[170:173], v[186:189], v[120:123]
	v_mfma_f32_16x16x32_bf16 v[112:115], v[178:181], v[186:189], v[112:115]
	v_mfma_f32_16x16x32_bf16 v[104:107], v[170:173], v[194:197], v[104:107]
	v_mfma_f32_16x16x32_bf16 v[96:99], v[178:181], v[194:197], v[96:99]
	v_mfma_f32_16x16x32_bf16 v[88:91], v[170:173], v[202:205], v[88:91]
	v_mfma_f32_16x16x32_bf16 v[80:83], v[178:181], v[202:205], v[80:83]
	v_mfma_f32_16x16x32_bf16 v[72:75], v[170:173], v[214:217], v[72:75]
	v_mfma_f32_16x16x32_bf16 v[64:67], v[178:181], v[214:217], v[64:67]
	s_barrier
	s_add_i32 s47, s38, s9
	v_lshl_add_u64 v[206:207], s[24:25], 0, v[132:133]
	s_mov_b32 m0, s47
	ds_read_b128 v[182:185], v153 offset:16384
	ds_read_b128 v[186:189], v153 offset:17408
	ds_read_b128 v[190:193], v153 offset:18432
	ds_read_b128 v[194:197], v153 offset:19456
	ds_read_b128 v[198:201], v153 offset:20480
	ds_read_b128 v[202:205], v153 offset:21504
	ds_read_b128 v[210:213], v153 offset:22528
	ds_read_b128 v[214:217], v153 offset:23552
	global_load_lds_dwordx4 v[206:207], off
	s_add_i32 m0, s47, 0x2000
	s_add_u32 s48, s24, 0x40000
	v_lshl_add_u64 v[218:219], s[24:25], 0, v[128:129]
	s_addc_u32 s49, s25, 0
	s_add_i32 s47, s39, s9
	global_load_lds_dwordx4 v[218:219], off
	v_lshl_add_u64 v[220:221], s[48:49], 0, v[132:133]
	s_mov_b32 m0, s47
	v_lshl_add_u64 v[222:223], s[26:27], 0, v[130:131]
	global_load_lds_dwordx4 v[220:221], off
	v_lshl_add_u64 v[220:221], s[48:49], 0, v[128:129]
	s_add_i32 m0, s47, 0x2000
	s_nop 0
	global_load_lds_dwordx4 v[220:221], off
	v_lshl_add_u64 v[220:221], s[26:27], 0, v[134:135]
	s_mov_b32 m0, s21
	s_nop 0
	global_load_lds_dwordx4 v[220:221], off
	s_mov_b32 m0, s30
	s_nop 0
	global_load_lds_dwordx4 v[222:223], off
	s_waitcnt vmcnt(8)
	s_waitcnt lgkmcnt(0)
	s_barrier
	s_waitcnt lgkmcnt(0)
	v_mfma_f32_16x16x32_bf16 v[60:63], v[144:147], v[182:185], 0
	v_mfma_f32_16x16x32_bf16 v[52:55], v[158:161], v[182:185], 0
	v_mfma_f32_16x16x32_bf16 v[44:47], v[144:147], v[190:193], 0
	v_mfma_f32_16x16x32_bf16 v[36:39], v[158:161], v[190:193], 0
	v_mfma_f32_16x16x32_bf16 v[28:31], v[144:147], v[198:201], 0
	v_mfma_f32_16x16x32_bf16 v[20:23], v[158:161], v[198:201], 0
	v_mfma_f32_16x16x32_bf16 v[12:15], v[144:147], v[210:213], 0
	v_mfma_f32_16x16x32_bf16 v[4:7], v[158:161], v[210:213], 0
	v_mfma_f32_16x16x32_bf16 v[60:63], v[154:157], v[186:189], v[60:63]
	v_mfma_f32_16x16x32_bf16 v[52:55], v[162:165], v[186:189], v[52:55]
	v_mfma_f32_16x16x32_bf16 v[44:47], v[154:157], v[194:197], v[44:47]
	v_mfma_f32_16x16x32_bf16 v[36:39], v[162:165], v[194:197], v[36:39]
	v_mfma_f32_16x16x32_bf16 v[28:31], v[154:157], v[202:205], v[28:31]
	v_mfma_f32_16x16x32_bf16 v[20:23], v[162:165], v[202:205], v[20:23]
	v_mfma_f32_16x16x32_bf16 v[12:15], v[154:157], v[214:217], v[12:15]
	v_mfma_f32_16x16x32_bf16 v[4:7], v[162:165], v[214:217], v[4:7]
	v_mfma_f32_16x16x32_bf16 v[56:59], v[166:169], v[182:185], 0
	v_mfma_f32_16x16x32_bf16 v[48:51], v[174:177], v[182:185], 0
	v_mfma_f32_16x16x32_bf16 v[40:43], v[166:169], v[190:193], 0
	v_mfma_f32_16x16x32_bf16 v[32:35], v[174:177], v[190:193], 0
	v_mfma_f32_16x16x32_bf16 v[24:27], v[166:169], v[198:201], 0
	v_mfma_f32_16x16x32_bf16 v[16:19], v[174:177], v[198:201], 0
	v_mfma_f32_16x16x32_bf16 v[8:11], v[166:169], v[210:213], 0
	v_mfma_f32_16x16x32_bf16 v[0:3], v[174:177], v[210:213], 0
	v_mfma_f32_16x16x32_bf16 v[56:59], v[170:173], v[186:189], v[56:59]
	v_mfma_f32_16x16x32_bf16 v[48:51], v[178:181], v[186:189], v[48:51]
	v_mfma_f32_16x16x32_bf16 v[40:43], v[170:173], v[194:197], v[40:43]
	v_mfma_f32_16x16x32_bf16 v[32:35], v[178:181], v[194:197], v[32:35]
	v_mfma_f32_16x16x32_bf16 v[24:27], v[170:173], v[202:205], v[24:27]
	v_mfma_f32_16x16x32_bf16 v[16:19], v[178:181], v[202:205], v[16:19]
	v_mfma_f32_16x16x32_bf16 v[8:11], v[170:173], v[214:217], v[8:11]
	v_mfma_f32_16x16x32_bf16 v[0:3], v[178:181], v[214:217], v[0:3]
	s_barrier
; #define PG8_STAGE(bufoff, gbase, voff) do { _Pragma("unroll") for (int _i = 0; _i < 2; ++_i) \
;         __builtin_amdgcn_global_load_lds((const unsigned*)((const char*)(gbase) + (voff)[_i]), (PG8_LAS unsigned*)(lds + (bufoff) + ldsw + _i * 8192), 16, 0, 0); } while (0)
; #define PG8_LDA(dst, b, h) do { _Pragma("unroll") for (int m = 0; m < 4; ++m) _Pragma("unroll") for (int k = 0; k < 2; ++k) dst[m][k] = *(const PG8_LAS bf16x8*)(lds + PG8_SA(b, h) + aoff + m * 2048 + k * 1024); } while (0)
; #define PG8_LDB(dst, b, h) do { _Pragma("unroll") for (int n = 0; n < 2; ++n) _Pragma("unroll") for (int k = 0; k < 2; ++k) dst[n][k] = *(const PG8_LAS bf16x8*)(lds + PG8_SB(b, h) + boff + n * 2048 + k * 1024); } while (0)
; #define PG8_MMA(ai, bj, At, Bt) do { __builtin_amdgcn_s_setprio(1); _Pragma("unroll") for (int m = 0; m < 4; ++m) _Pragma("unroll") for (int n = 0; n < 2; ++n) _Pragma("unroll") for (int k = 0; k < 2; ++k) \
;         acc[ai][bj][m][n] = __builtin_amdgcn_mfma_f32_16x16x32_bf16(Bt[n][k], At[m][k], acc[ai][bj][m][n], 0, 0, 0); __builtin_amdgcn_s_setprio(0); } while (0)
; #define PG8_WAIT_V(n) asm volatile("s_waitcnt vmcnt(" #n ")" ::: "memory")
; #define PG8_WAIT_L(n) asm volatile("s_waitcnt lgkmcnt(" #n ")" ::: "memory")
; #define PG8_BAR __builtin_amdgcn_s_barrier()
; #define PG8_SCHED __builtin_amdgcn_sched_barrier(0)
; template <class Epi, class Sched, bool ALIGN_EPI = false, bool SP2 = false>
; __device__ __forceinline__ void gemm_phase(PG8_LAS unsigned char* lds, const Gemm g, const Sched& S, const Epi& E, const int wid) {
;     ...
;             PG8_LDB(B0, 1, 0); PG8_LDB(B1, 1, 1); PG8_SCHED; PG8_LDA(At, 1, 0); PG8_STAGE(PG8_SA(0, 1), a2 + hstep, voffA);
;             PG8_WAIT_V(8); PG8_WAIT_L(0); PG8_BAR; PG8_MMA(0, 0, At, B0); PG8_MMA(0, 1, At, B1); PG8_BAR; PG8_SCHED;
	s_add_i32 s47, 0, 0x18000
	s_add_i32 s48, 0, 0x1c000
	v_add_u32_e32 v162, s47, v149
	v_add_u32_e32 v178, s48, v149
	ds_read_b128 v[144:147], v162
	ds_read_b128 v[154:157], v162 offset:1024
	ds_read_b128 v[158:161], v162 offset:2048
	ds_read_b128 v[162:165], v162 offset:3072
	ds_read_b128 v[166:169], v178
	ds_read_b128 v[170:173], v178 offset:1024
	ds_read_b128 v[174:177], v178 offset:2048
	ds_read_b128 v[178:181], v178 offset:3072
	s_add_u32 s26, s26, 0x40000
	s_addc_u32 s27, s27, 0
	s_mov_b32 m0, s31
	v_lshl_add_u64 v[224:225], s[26:27], 0, v[134:135]
	ds_read_b128 v[182:185], v153 offset:32768
	ds_read_b128 v[186:189], v153 offset:33792
	ds_read_b128 v[190:193], v153 offset:34816
	ds_read_b128 v[194:197], v153 offset:35840
	ds_read_b128 v[198:201], v153 offset:36864
	ds_read_b128 v[202:205], v153 offset:37888
	ds_read_b128 v[210:213], v153 offset:38912
	ds_read_b128 v[214:217], v153 offset:39936
	global_load_lds_dwordx4 v[224:225], off
	v_lshl_add_u64 v[224:225], s[26:27], 0, v[130:131]
	s_mov_b32 m0, s33
	s_nop 0
	global_load_lds_dwordx4 v[224:225], off
	s_waitcnt vmcnt(8)
	s_waitcnt lgkmcnt(0)
	s_barrier
	s_waitcnt lgkmcnt(0)
	v_mfma_f32_16x16x32_bf16 v[124:127], v[144:147], v[182:185], v[124:127]
	v_mfma_f32_16x16x32_bf16 v[116:119], v[158:161], v[182:185], v[116:119]
	v_mfma_f32_16x16x32_bf16 v[108:111], v[144:147], v[190:193], v[108:111]
	v_mfma_f32_16x16x32_bf16 v[100:103], v[158:161], v[190:193], v[100:103]
	v_mfma_f32_16x16x32_bf16 v[92:95], v[144:147], v[198:201], v[92:95]
	v_mfma_f32_16x16x32_bf16 v[84:87], v[158:161], v[198:201], v[84:87]
	v_mfma_f32_16x16x32_bf16 v[76:79], v[144:147], v[210:213], v[76:79]
	v_mfma_f32_16x16x32_bf16 v[68:71], v[158:161], v[210:213], v[68:71]
	v_mfma_f32_16x16x32_bf16 v[124:127], v[154:157], v[186:189], v[124:127]
	v_mfma_f32_16x16x32_bf16 v[116:119], v[162:165], v[186:189], v[116:119]
	v_mfma_f32_16x16x32_bf16 v[108:111], v[154:157], v[194:197], v[108:111]
	v_mfma_f32_16x16x32_bf16 v[100:103], v[162:165], v[194:197], v[100:103]
	v_mfma_f32_16x16x32_bf16 v[92:95], v[154:157], v[202:205], v[92:95]
	v_mfma_f32_16x16x32_bf16 v[84:87], v[162:165], v[202:205], v[84:87]
	v_mfma_f32_16x16x32_bf16 v[76:79], v[154:157], v[214:217], v[76:79]
	v_mfma_f32_16x16x32_bf16 v[68:71], v[162:165], v[214:217], v[68:71]
	v_mfma_f32_16x16x32_bf16 v[120:123], v[166:169], v[182:185], v[120:123]
	v_mfma_f32_16x16x32_bf16 v[112:115], v[174:177], v[182:185], v[112:115]
	v_mfma_f32_16x16x32_bf16 v[104:107], v[166:169], v[190:193], v[104:107]
	v_mfma_f32_16x16x32_bf16 v[96:99], v[174:177], v[190:193], v[96:99]
	v_mfma_f32_16x16x32_bf16 v[88:91], v[166:169], v[198:201], v[88:91]
	v_mfma_f32_16x16x32_bf16 v[80:83], v[174:177], v[198:201], v[80:83]
	v_mfma_f32_16x16x32_bf16 v[72:75], v[166:169], v[210:213], v[72:75]
	v_mfma_f32_16x16x32_bf16 v[64:67], v[174:177], v[210:213], v[64:67]
	v_mfma_f32_16x16x32_bf16 v[120:123], v[170:173], v[186:189], v[120:123]
	v_mfma_f32_16x16x32_bf16 v[112:115], v[178:181], v[186:189], v[112:115]
	v_mfma_f32_16x16x32_bf16 v[104:107], v[170:173], v[194:197], v[104:107]
	v_mfma_f32_16x16x32_bf16 v[96:99], v[178:181], v[194:197], v[96:99]
	v_mfma_f32_16x16x32_bf16 v[88:91], v[170:173], v[202:205], v[88:91]
	v_mfma_f32_16x16x32_bf16 v[80:83], v[178:181], v[202:205], v[80:83]
	v_mfma_f32_16x16x32_bf16 v[72:75], v[170:173], v[214:217], v[72:75]
	v_mfma_f32_16x16x32_bf16 v[64:67], v[178:181], v[214:217], v[64:67]
	s_barrier
; #define PG8_STAGE(bufoff, gbase, voff) do { _Pragma("unroll") for (int _i = 0; _i < 2; ++_i) \
;         __builtin_amdgcn_global_load_lds((const unsigned*)((const char*)(gbase) + (voff)[_i]), (PG8_LAS unsigned*)(lds + (bufoff) + ldsw + _i * 8192), 16, 0, 0); } while (0)
; #define PG8_LDA(dst, b, h) do { _Pragma("unroll") for (int m = 0; m < 4; ++m) _Pragma("unroll") for (int k = 0; k < 2; ++k) dst[m][k] = *(const PG8_LAS bf16x8*)(lds + PG8_SA(b, h) + aoff + m * 2048 + k * 1024); } while (0)
; #define PG8_MMA(ai, bj, At, Bt) do { __builtin_amdgcn_s_setprio(1); _Pragma("unroll") for (int m = 0; m < 4; ++m) _Pragma("unroll") for (int n = 0; n < 2; ++n) _Pragma("unroll") for (int k = 0; k < 2; ++k) \
;         acc[ai][bj][m][n] = __builtin_amdgcn_mfma_f32_16x16x32_bf16(Bt[n][k], At[m][k], acc[ai][bj][m][n], 0, 0, 0); __builtin_amdgcn_s_setprio(0); } while (0)
; #define PG8_WAIT_V(n) asm volatile("s_waitcnt vmcnt(" #n ")" ::: "memory")
; #define PG8_WAIT_L(n) asm volatile("s_waitcnt lgkmcnt(" #n ")" ::: "memory")
; #define PG8_BAR __builtin_amdgcn_s_barrier()
; #define PG8_SCHED __builtin_amdgcn_sched_barrier(0)
; template <class Epi, class Sched, bool ALIGN_EPI = false, bool SP2 = false>
; __device__ __forceinline__ void gemm_phase(PG8_LAS unsigned char* lds, const Gemm g, const Sched& S, const Epi& E, const int wid) {
;     ...
;             PG8_LDA(At, 1, 1); PG8_STAGE(PG8_SB(1, 0), b3, voffB); PG8_STAGE(PG8_SB(1, 1), b3 + hstep, voffB); PG8_STAGE(PG8_SA(1, 0), a3, voffA);
;             PG8_WAIT_V(8); PG8_WAIT_L(0); PG8_BAR; PG8_MMA(1, 0, At, B0); PG8_MMA(1, 1, At, B1); PG8_BAR; PG8_SCHED;
	s_add_i32 s26, s47, s9
	v_lshl_add_u64 v[206:207], v[206:207], 0, s[2:3]
	s_mov_b32 m0, s26
	ds_read_b128 v[182:185], v153 offset:49152
	ds_read_b128 v[186:189], v153 offset:50176
	ds_read_b128 v[190:193], v153 offset:51200
	ds_read_b128 v[194:197], v153 offset:52224
	ds_read_b128 v[198:201], v153 offset:53248
	ds_read_b128 v[202:205], v153 offset:54272
	ds_read_b128 v[210:213], v153 offset:55296
	ds_read_b128 v[214:217], v153 offset:56320
	global_load_lds_dwordx4 v[206:207], off
	s_add_i32 m0, s26, 0x2000
	s_add_u32 s24, s24, 0x40080
	v_lshl_add_u64 v[206:207], v[218:219], 0, s[2:3]
	s_addc_u32 s25, s25, 0
	s_add_i32 s26, s48, s9
	global_load_lds_dwordx4 v[206:207], off
	v_lshl_add_u64 v[206:207], s[24:25], 0, v[132:133]
	s_mov_b32 m0, s26
	s_nop 0
	global_load_lds_dwordx4 v[206:207], off
	v_lshl_add_u64 v[206:207], s[24:25], 0, v[128:129]
	s_add_i32 m0, s26, 0x2000
	s_nop 0
	global_load_lds_dwordx4 v[206:207], off
	v_lshl_add_u64 v[206:207], v[220:221], 0, s[2:3]
	s_mov_b32 m0, s35
	s_nop 0
	global_load_lds_dwordx4 v[206:207], off
	v_lshl_add_u64 v[206:207], v[222:223], 0, s[2:3]
	s_mov_b32 m0, s36
	s_nop 0
	global_load_lds_dwordx4 v[206:207], off
	s_waitcnt vmcnt(8)
	s_waitcnt lgkmcnt(0)
	s_barrier
	s_waitcnt lgkmcnt(0)
	v_mfma_f32_16x16x32_bf16 v[60:63], v[144:147], v[182:185], v[60:63]
	v_mfma_f32_16x16x32_bf16 v[52:55], v[158:161], v[182:185], v[52:55]
	v_mfma_f32_16x16x32_bf16 v[44:47], v[144:147], v[190:193], v[44:47]
	v_mfma_f32_16x16x32_bf16 v[36:39], v[158:161], v[190:193], v[36:39]
	v_mfma_f32_16x16x32_bf16 v[28:31], v[144:147], v[198:201], v[28:31]
	v_mfma_f32_16x16x32_bf16 v[20:23], v[158:161], v[198:201], v[20:23]
	v_mfma_f32_16x16x32_bf16 v[12:15], v[144:147], v[210:213], v[12:15]
	v_mfma_f32_16x16x32_bf16 v[4:7], v[158:161], v[210:213], v[4:7]
	v_mfma_f32_16x16x32_bf16 v[60:63], v[154:157], v[186:189], v[60:63]
	v_mfma_f32_16x16x32_bf16 v[52:55], v[162:165], v[186:189], v[52:55]
	v_mfma_f32_16x16x32_bf16 v[44:47], v[154:157], v[194:197], v[44:47]
	v_mfma_f32_16x16x32_bf16 v[36:39], v[162:165], v[194:197], v[36:39]
	v_mfma_f32_16x16x32_bf16 v[28:31], v[154:157], v[202:205], v[28:31]
	v_mfma_f32_16x16x32_bf16 v[20:23], v[162:165], v[202:205], v[20:23]
	v_mfma_f32_16x16x32_bf16 v[12:15], v[154:157], v[214:217], v[12:15]
	v_mfma_f32_16x16x32_bf16 v[4:7], v[162:165], v[214:217], v[4:7]
	v_mfma_f32_16x16x32_bf16 v[56:59], v[166:169], v[182:185], v[56:59]
	v_mfma_f32_16x16x32_bf16 v[48:51], v[174:177], v[182:185], v[48:51]
	v_mfma_f32_16x16x32_bf16 v[40:43], v[166:169], v[190:193], v[40:43]
	v_mfma_f32_16x16x32_bf16 v[32:35], v[174:177], v[190:193], v[32:35]
	v_mfma_f32_16x16x32_bf16 v[24:27], v[166:169], v[198:201], v[24:27]
	v_mfma_f32_16x16x32_bf16 v[16:19], v[174:177], v[198:201], v[16:19]
	v_mfma_f32_16x16x32_bf16 v[8:11], v[166:169], v[210:213], v[8:11]
	v_mfma_f32_16x16x32_bf16 v[0:3], v[174:177], v[210:213], v[0:3]
	v_mfma_f32_16x16x32_bf16 v[56:59], v[170:173], v[186:189], v[56:59]
	v_mfma_f32_16x16x32_bf16 v[48:51], v[178:181], v[186:189], v[48:51]
	v_mfma_f32_16x16x32_bf16 v[40:43], v[170:173], v[194:197], v[40:43]
	v_mfma_f32_16x16x32_bf16 v[32:35], v[178:181], v[194:197], v[32:35]
	v_mfma_f32_16x16x32_bf16 v[24:27], v[170:173], v[202:205], v[24:27]
	v_mfma_f32_16x16x32_bf16 v[16:19], v[178:181], v[202:205], v[16:19]
	v_mfma_f32_16x16x32_bf16 v[8:11], v[170:173], v[214:217], v[8:11]
	v_mfma_f32_16x16x32_bf16 v[0:3], v[178:181], v[214:217], v[0:3]
	s_barrier
	s_add_i32 s46, s46, 2
	s_add_u32 s22, s22, 0x100
	s_addc_u32 s23, s23, 0
	s_add_u32 s44, s44, 0x100
	s_addc_u32 s45, s45, 0
	s_cmp_gt_u32 s46, 13
	s_cbranch_scc0 .LBB0_1912
	s_branch .Lkp_exit_4
	.p2align 6

; template <class Epi, class Sched, bool ALIGN_EPI = false, bool SP2 = false>
; __device__ __forceinline__ void gemm_phase(PG8_LAS unsigned char* lds, const Gemm g, const Sched& S, const Epi& E, const int wid) {
;     ...
;         const char* nA = has_next ? (const char*)g.A + (size_t)nxt.pm * tstep : cA; const char* nB = has_next ? (const char*)g.Bt + (size_t)nxt.pn * tstep : cB;
;         for (int t = 0; t < nt; t += 2) {
;             const bool last = (t == nt - 2);
;             const char* a1 = cA + (size_t)(t + 1) * kstep;
;             const char* a2 = last ? nA : cA + (size_t)(t + 2) * kstep; const char* b2 = last ? nB : cB + (size_t)(t + 2) * kstep;
;             const char* a3 = a2 + kstep; const char* b3 = b2 + kstep;
.LBB0_2459:
	s_add_u32 s40, s14, 0x100
	s_addc_u32 s41, s15, 0
	v_lshl_add_u64 v[144:145], s[8:9], 0, v[136:137]
	v_lshl_add_u64 v[146:147], s[8:9], 0, v[138:139]
	s_mov_b32 s42, -2
	s_mov_b64 s[14:15], 0
	.p2align 6
